# HID workspace stored in 16x32-subtile tiled layout (P7+P6 EpiUp stores contiguous 1KB per wave-store; P8 A-operand LDS-DMA addressing adapted); P7 ssq prefetch
# speedup vs baseline: 1.0138x; 1.0138x over previous
; __device__ __forceinline__ u32x4 pack8(const f32x4 a, const f32x4 b) { u32x4 w; w.x = cvt_pk_bf16(a[0], a[1]); w.y = cvt_pk_bf16(a[2], a[3]); w.z = cvt_pk_bf16(b[0], b[1]); w.w = cvt_pk_bf16(b[2], b[3]); return w; }
;     __device__ __forceinline__ void operator()(AccRef acc, const Unit& u, int wr, int wc, int fr, int fq) const {
; #pragma unroll
;         for (int ai = 0; ai < 2; ++ai)
; #pragma unroll
;             for (int m = 0; m < 4; ++m) { const int row = u.pm * 256 + ai * 128 + wr * 64 + m * 16 + fr;
;                 const float r2 = rsqrtf(ssq[row] * (1.0f / D) + EPS);
; #pragma unroll
;                 for (int bj = 0; bj < 2; ++bj) { const int col = u.pn * 256 + bj * 128 + wc * 32 + 8 * fq;
;                     f32x4 h0 = acc[ai][bj][m][0] * r2, h1 = acc[ai][bj][m][1] * r2;
; #pragma unroll
;                     for (int q = 0; q < 4; ++q) { const float a = fmaxf(h0[q], 0.f), b = fmaxf(h1[q], 0.f); h0[q] = a * a; h1[q] = b * b; }
;                     __builtin_nontemporal_store(pack8(h0, h1), (u32x4*)(HID + (size_t)row * DFF + col)); } }
;     }
.LBB0_764:
	v_lshl_add_u32 v128, s4, 8, v142
	v_mov_b32_e32 v129, 0
	v_lshl_add_u64 v[132:133], v[128:129], 2, s[30:31]
	v_and_b32_e32 v128, -16, v128
	global_load_dword v130, v[132:133], off
	v_mov_b32_e32 v134, 0x358637bd
	s_mov_b32 s0, 0x800000
	v_lshl_or_b32 v131, s2, 8, v137
	v_or_b32_e32 v135, s23, v131
	v_readlane_b32 s4, v242, 6
	v_lshlrev_b64 v[138:139], 14, v[128:129]
	v_readlane_b32 s5, v242, 7
	v_mov_b32_e32 v131, v129
	s_waitcnt vmcnt(0)
	v_fmamk_f32 v130, v130, 0x3a000000, v134
	v_mul_f32_e32 v137, 0x4b800000, v130
	v_cmp_gt_f32_e32 vcc, s0, v130
	v_lshl_add_u64 v[138:139], s[4:5], 0, v[138:139]
	s_nop 0
	v_cndmask_b32_e32 v130, v130, v137, vcc
	v_rsq_f32_e32 v137, v130
	v_lshrrev_b32_e32 v130, 5, v135
	v_lshlrev_b32_e32 v130, 10, v130
	v_and_b32_e32 v135, 24, v135
	v_lshl_add_u32 v130, v135, 1, v130
	v_and_b32_e32 v135, 15, v136
	v_lshl_add_u32 v130, v135, 6, v130
	v_add_u32_e32 v130, 0x1000, v130
	v_lshl_add_u64 v[138:139], v[138:139], 0, v[130:131]
	v_mul_f32_e32 v135, 0x45800000, v137
	v_cndmask_b32_e32 v140, v137, v135, vcc
	v_pk_mul_f32 v[126:127], v[126:127], v[140:141] op_sel_hi:[1,0]
	v_pk_mul_f32 v[124:125], v[124:125], v[140:141] op_sel_hi:[1,0]
	v_pk_mul_f32 v[122:123], v[122:123], v[140:141] op_sel_hi:[1,0]
	v_pk_mul_f32 v[120:121], v[120:121], v[140:141] op_sel_hi:[1,0]
	v_pk_mul_f32 v[118:119], v[118:119], v[140:141] op_sel_hi:[1,0]
	v_pk_mul_f32 v[114:115], v[114:115], v[140:141] op_sel_hi:[1,0]
	v_pk_mul_f32 v[112:113], v[112:113], v[140:141] op_sel_hi:[1,0]
	v_pk_mul_f32 v[116:117], v[116:117], v[140:141] op_sel_hi:[1,0]
	v_max_f32_e32 v124, 0, v124
	v_max_f32_e32 v120, 0, v120
	v_max_f32_e32 v125, 0, v125
	v_max_f32_e32 v121, 0, v121
	v_max_f32_e32 v126, 0, v126
	v_max_f32_e32 v122, 0, v122
	v_max_f32_e32 v127, 0, v127
	v_max_f32_e32 v123, 0, v123
	v_max_f32_e32 v112, 0, v112
	v_max_f32_e32 v113, 0, v113
	v_max_f32_e32 v118, 0, v118
	v_max_f32_e32 v114, 0, v114
	v_max_f32_e32 v115, 0, v115
	v_max_f32_e32 v116, 0, v116
	v_max_f32_e32 v117, 0, v117
	v_max_f32_e32 v119, 0, v119
	v_mul_f32_e32 v124, v124, v124
	v_mul_f32_e32 v120, v120, v120
	v_mul_f32_e32 v125, v125, v125
	v_mul_f32_e32 v121, v121, v121
	v_mul_f32_e32 v126, v126, v126
	v_mul_f32_e32 v122, v122, v122
	v_mul_f32_e32 v127, v127, v127
	v_mul_f32_e32 v123, v123, v123
	v_mul_f32_e32 v135, v112, v112
	v_mul_f32_e32 v137, v113, v113
	v_mul_f32_e32 v118, v118, v118
	v_mul_f32_e32 v140, v114, v114
	v_mul_f32_e32 v141, v115, v115
	v_cvt_pk_bf16_f32 v112, v124, v125
	v_cvt_pk_bf16_f32 v113, v126, v127
	v_cvt_pk_bf16_f32 v114, v120, v121
	v_cvt_pk_bf16_f32 v115, v122, v123
	v_mul_f32_e32 v116, v116, v116
	v_mul_f32_e32 v117, v117, v117
	v_mul_f32_e32 v119, v119, v119
	global_store_dwordx4 v[138:139], v[112:115], off offset:-4096 nt
	s_nop 1
	v_cvt_pk_bf16_f32 v112, v116, v117
	v_cvt_pk_bf16_f32 v113, v118, v119
	v_cvt_pk_bf16_f32 v114, v135, v137
	v_cvt_pk_bf16_f32 v115, v140, v141
	global_load_dword v118, v[132:133], off offset:64
	v_or_b32_e32 v116, 16, v128
	global_store_dwordx4 v[138:139], v[112:115], off nt
	v_mov_b32_e32 v117, v129
	v_lshlrev_b64 v[116:117], 14, v[116:117]
	v_lshl_add_u64 v[116:117], s[4:5], 0, v[116:117]
	v_lshl_add_u64 v[116:117], v[116:117], 0, v[130:131]
	s_waitcnt vmcnt(1)
	v_fmamk_f32 v118, v118, 0x3a000000, v134
	v_mul_f32_e32 v119, 0x4b800000, v118
	v_cmp_gt_f32_e32 vcc, s0, v118
	s_nop 1
	v_cndmask_b32_e32 v118, v118, v119, vcc
	v_rsq_f32_e32 v118, v118
	s_nop 0
	v_mul_f32_e32 v112, 0x45800000, v118
	v_cndmask_b32_e32 v112, v118, v112, vcc
	v_pk_mul_f32 v[110:111], v[110:111], v[112:113] op_sel_hi:[1,0]
	v_pk_mul_f32 v[108:109], v[108:109], v[112:113] op_sel_hi:[1,0]
	v_pk_mul_f32 v[106:107], v[106:107], v[112:113] op_sel_hi:[1,0]
	v_pk_mul_f32 v[104:105], v[104:105], v[112:113] op_sel_hi:[1,0]
	v_pk_mul_f32 v[102:103], v[102:103], v[112:113] op_sel_hi:[1,0]
	v_pk_mul_f32 v[98:99], v[98:99], v[112:113] op_sel_hi:[1,0]
	v_pk_mul_f32 v[96:97], v[96:97], v[112:113] op_sel_hi:[1,0]
	v_pk_mul_f32 v[100:101], v[100:101], v[112:113] op_sel_hi:[1,0]
	v_max_f32_e32 v108, 0, v108
	v_max_f32_e32 v104, 0, v104
	v_max_f32_e32 v109, 0, v109
	v_max_f32_e32 v105, 0, v105
	v_max_f32_e32 v110, 0, v110
	v_max_f32_e32 v106, 0, v106
	v_max_f32_e32 v111, 0, v111
	v_max_f32_e32 v107, 0, v107
	v_max_f32_e32 v96, 0, v96
	v_max_f32_e32 v97, 0, v97
	v_max_f32_e32 v102, 0, v102
	v_max_f32_e32 v98, 0, v98
	v_max_f32_e32 v99, 0, v99
	v_max_f32_e32 v100, 0, v100
	v_max_f32_e32 v101, 0, v101
	v_max_f32_e32 v103, 0, v103
	v_mul_f32_e32 v108, v108, v108
	v_mul_f32_e32 v104, v104, v104
	v_mul_f32_e32 v109, v109, v109
	v_mul_f32_e32 v105, v105, v105
	v_mul_f32_e32 v110, v110, v110
	v_mul_f32_e32 v106, v106, v106
	v_mul_f32_e32 v111, v111, v111
	v_mul_f32_e32 v107, v107, v107
	v_mul_f32_e32 v112, v96, v96
	v_mul_f32_e32 v113, v97, v97
	v_mul_f32_e32 v102, v102, v102
	v_mul_f32_e32 v114, v98, v98
	v_mul_f32_e32 v115, v99, v99
	v_cvt_pk_bf16_f32 v96, v108, v109
	v_cvt_pk_bf16_f32 v97, v110, v111
	v_cvt_pk_bf16_f32 v98, v104, v105
	v_cvt_pk_bf16_f32 v99, v106, v107
	v_mul_f32_e32 v100, v100, v100
	v_mul_f32_e32 v101, v101, v101
	v_mul_f32_e32 v103, v103, v103
	global_store_dwordx4 v[116:117], v[96:99], off offset:-4096 nt
	s_nop 1
	v_cvt_pk_bf16_f32 v96, v100, v101
	v_cvt_pk_bf16_f32 v97, v102, v103
	v_cvt_pk_bf16_f32 v98, v112, v113
	v_cvt_pk_bf16_f32 v99, v114, v115
	global_load_dword v102, v[132:133], off offset:128
	v_or_b32_e32 v100, 32, v128
	global_store_dwordx4 v[116:117], v[96:99], off nt
	v_mov_b32_e32 v101, v129
	v_lshlrev_b64 v[100:101], 14, v[100:101]
	v_lshl_add_u64 v[100:101], s[4:5], 0, v[100:101]
	v_lshl_add_u64 v[100:101], v[100:101], 0, v[130:131]
	s_waitcnt vmcnt(1)
; __device__ __forceinline__ u32x4 pack8(const f32x4 a, const f32x4 b) { u32x4 w; w.x = cvt_pk_bf16(a[0], a[1]); w.y = cvt_pk_bf16(a[2], a[3]); w.z = cvt_pk_bf16(b[0], b[1]); w.w = cvt_pk_bf16(b[2], b[3]); return w; }
;     __device__ __forceinline__ void operator()(AccRef acc, const Unit& u, int wr, int wc, int fr, int fq) const {
; #pragma unroll
;         for (int ai = 0; ai < 2; ++ai)
; #pragma unroll
;             for (int m = 0; m < 4; ++m) { const int row = u.pm * 256 + ai * 128 + wr * 64 + m * 16 + fr;
;                 const float r2 = rsqrtf(ssq[row] * (1.0f / D) + EPS);
; #pragma unroll
;                 for (int bj = 0; bj < 2; ++bj) { const int col = u.pn * 256 + bj * 128 + wc * 32 + 8 * fq;
;                     f32x4 h0 = acc[ai][bj][m][0] * r2, h1 = acc[ai][bj][m][1] * r2;
; #pragma unroll
;                     for (int q = 0; q < 4; ++q) { const float a = fmaxf(h0[q], 0.f), b = fmaxf(h1[q], 0.f); h0[q] = a * a; h1[q] = b * b; }
;                     __builtin_nontemporal_store(pack8(h0, h1), (u32x4*)(HID + (size_t)row * DFF + col)); } }
;     }
	v_fmamk_f32 v102, v102, 0x3a000000, v134
	v_mul_f32_e32 v103, 0x4b800000, v102
	v_cmp_gt_f32_e32 vcc, s0, v102
	s_nop 1
	v_cndmask_b32_e32 v102, v102, v103, vcc
	v_rsq_f32_e32 v102, v102
	s_nop 0
	v_mul_f32_e32 v96, 0x45800000, v102
	v_cndmask_b32_e32 v96, v102, v96, vcc
	v_pk_mul_f32 v[94:95], v[94:95], v[96:97] op_sel_hi:[1,0]
	v_pk_mul_f32 v[92:93], v[92:93], v[96:97] op_sel_hi:[1,0]
	v_pk_mul_f32 v[90:91], v[90:91], v[96:97] op_sel_hi:[1,0]
	v_pk_mul_f32 v[88:89], v[88:89], v[96:97] op_sel_hi:[1,0]
	v_pk_mul_f32 v[86:87], v[86:87], v[96:97] op_sel_hi:[1,0]
	v_pk_mul_f32 v[82:83], v[82:83], v[96:97] op_sel_hi:[1,0]
	v_pk_mul_f32 v[80:81], v[80:81], v[96:97] op_sel_hi:[1,0]
	v_pk_mul_f32 v[84:85], v[84:85], v[96:97] op_sel_hi:[1,0]
	v_max_f32_e32 v92, 0, v92
	v_max_f32_e32 v88, 0, v88
	v_max_f32_e32 v93, 0, v93
	v_max_f32_e32 v89, 0, v89
	v_max_f32_e32 v94, 0, v94
	v_max_f32_e32 v90, 0, v90
	v_max_f32_e32 v95, 0, v95
	v_max_f32_e32 v91, 0, v91
	v_max_f32_e32 v80, 0, v80
	v_max_f32_e32 v81, 0, v81
	v_max_f32_e32 v86, 0, v86
	v_max_f32_e32 v82, 0, v82
	v_max_f32_e32 v83, 0, v83
	v_max_f32_e32 v84, 0, v84
	v_max_f32_e32 v85, 0, v85
	v_max_f32_e32 v87, 0, v87
	v_mul_f32_e32 v92, v92, v92
	v_mul_f32_e32 v88, v88, v88
	v_mul_f32_e32 v93, v93, v93
	v_mul_f32_e32 v89, v89, v89
	v_mul_f32_e32 v94, v94, v94
	v_mul_f32_e32 v90, v90, v90
	v_mul_f32_e32 v95, v95, v95
	v_mul_f32_e32 v91, v91, v91
	v_mul_f32_e32 v96, v80, v80
	v_mul_f32_e32 v97, v81, v81
	v_mul_f32_e32 v86, v86, v86
	v_mul_f32_e32 v98, v82, v82
	v_mul_f32_e32 v99, v83, v83
	v_cvt_pk_bf16_f32 v80, v92, v93
	v_cvt_pk_bf16_f32 v81, v94, v95
	v_cvt_pk_bf16_f32 v82, v88, v89
	v_cvt_pk_bf16_f32 v83, v90, v91
	v_mul_f32_e32 v84, v84, v84
	v_mul_f32_e32 v85, v85, v85
	v_mul_f32_e32 v87, v87, v87
	global_store_dwordx4 v[100:101], v[80:83], off offset:-4096 nt
	s_nop 1
	v_cvt_pk_bf16_f32 v80, v84, v85
	v_cvt_pk_bf16_f32 v81, v86, v87
	v_cvt_pk_bf16_f32 v82, v96, v97
	v_cvt_pk_bf16_f32 v83, v98, v99
	global_load_dword v86, v[132:133], off offset:192
	v_or_b32_e32 v84, 48, v128
	global_store_dwordx4 v[100:101], v[80:83], off nt
	v_mov_b32_e32 v85, v129
	v_lshlrev_b64 v[84:85], 14, v[84:85]
	v_lshl_add_u64 v[84:85], s[4:5], 0, v[84:85]
	v_lshl_add_u64 v[84:85], v[84:85], 0, v[130:131]
	s_waitcnt vmcnt(1)
	v_fmamk_f32 v86, v86, 0x3a000000, v134
	v_mul_f32_e32 v87, 0x4b800000, v86
	v_cmp_gt_f32_e32 vcc, s0, v86
	s_nop 1
	v_cndmask_b32_e32 v86, v86, v87, vcc
	v_rsq_f32_e32 v86, v86
	s_nop 0
	v_mul_f32_e32 v80, 0x45800000, v86
	v_cndmask_b32_e32 v80, v86, v80, vcc
	v_pk_mul_f32 v[78:79], v[78:79], v[80:81] op_sel_hi:[1,0]
	v_pk_mul_f32 v[76:77], v[76:77], v[80:81] op_sel_hi:[1,0]
	v_pk_mul_f32 v[74:75], v[74:75], v[80:81] op_sel_hi:[1,0]
	v_pk_mul_f32 v[72:73], v[72:73], v[80:81] op_sel_hi:[1,0]
	v_pk_mul_f32 v[70:71], v[70:71], v[80:81] op_sel_hi:[1,0]
	v_pk_mul_f32 v[66:67], v[66:67], v[80:81] op_sel_hi:[1,0]
	v_pk_mul_f32 v[64:65], v[64:65], v[80:81] op_sel_hi:[1,0]
	v_pk_mul_f32 v[68:69], v[68:69], v[80:81] op_sel_hi:[1,0]
	v_max_f32_e32 v76, 0, v76
	v_max_f32_e32 v72, 0, v72
	v_max_f32_e32 v77, 0, v77
	v_max_f32_e32 v73, 0, v73
	v_max_f32_e32 v78, 0, v78
	v_max_f32_e32 v74, 0, v74
	v_max_f32_e32 v79, 0, v79
	v_max_f32_e32 v75, 0, v75
	v_max_f32_e32 v64, 0, v64
	v_max_f32_e32 v65, 0, v65
	v_max_f32_e32 v70, 0, v70
	v_max_f32_e32 v66, 0, v66
	v_max_f32_e32 v67, 0, v67
	v_max_f32_e32 v68, 0, v68
	v_max_f32_e32 v69, 0, v69
	v_max_f32_e32 v71, 0, v71
	v_mul_f32_e32 v76, v76, v76
	v_mul_f32_e32 v72, v72, v72
	v_mul_f32_e32 v77, v77, v77
	v_mul_f32_e32 v73, v73, v73
	v_mul_f32_e32 v78, v78, v78
	v_mul_f32_e32 v74, v74, v74
	v_mul_f32_e32 v79, v79, v79
	v_mul_f32_e32 v75, v75, v75
	v_mul_f32_e32 v80, v64, v64
	v_mul_f32_e32 v81, v65, v65
	v_mul_f32_e32 v70, v70, v70
	v_mul_f32_e32 v82, v66, v66
	v_mul_f32_e32 v83, v67, v67
	v_cvt_pk_bf16_f32 v64, v76, v77
	v_cvt_pk_bf16_f32 v65, v78, v79
	v_cvt_pk_bf16_f32 v66, v72, v73
	v_cvt_pk_bf16_f32 v67, v74, v75
	v_mul_f32_e32 v68, v68, v68
	v_mul_f32_e32 v69, v69, v69
	v_mul_f32_e32 v71, v71, v71
	global_store_dwordx4 v[84:85], v[64:67], off offset:-4096 nt
	s_nop 1
	v_cvt_pk_bf16_f32 v64, v68, v69
	v_cvt_pk_bf16_f32 v65, v70, v71
	v_cvt_pk_bf16_f32 v66, v80, v81
	v_cvt_pk_bf16_f32 v67, v82, v83
	global_load_dword v70, v[132:133], off offset:512
	v_add_u32_e32 v68, 0x80, v128
	global_store_dwordx4 v[84:85], v[64:67], off nt
	v_mov_b32_e32 v69, v129
	v_lshlrev_b64 v[68:69], 14, v[68:69]
	v_lshl_add_u64 v[68:69], s[4:5], 0, v[68:69]
	v_lshl_add_u64 v[68:69], v[68:69], 0, v[130:131]
	s_waitcnt vmcnt(1)
; __device__ __forceinline__ u32x4 pack8(const f32x4 a, const f32x4 b) { u32x4 w; w.x = cvt_pk_bf16(a[0], a[1]); w.y = cvt_pk_bf16(a[2], a[3]); w.z = cvt_pk_bf16(b[0], b[1]); w.w = cvt_pk_bf16(b[2], b[3]); return w; }
;     __device__ __forceinline__ void operator()(AccRef acc, const Unit& u, int wr, int wc, int fr, int fq) const {
; #pragma unroll
;         for (int ai = 0; ai < 2; ++ai)
; #pragma unroll
;             for (int m = 0; m < 4; ++m) { const int row = u.pm * 256 + ai * 128 + wr * 64 + m * 16 + fr;
;                 const float r2 = rsqrtf(ssq[row] * (1.0f / D) + EPS);
; #pragma unroll
;                 for (int bj = 0; bj < 2; ++bj) { const int col = u.pn * 256 + bj * 128 + wc * 32 + 8 * fq;
;                     f32x4 h0 = acc[ai][bj][m][0] * r2, h1 = acc[ai][bj][m][1] * r2;
; #pragma unroll
;                     for (int q = 0; q < 4; ++q) { const float a = fmaxf(h0[q], 0.f), b = fmaxf(h1[q], 0.f); h0[q] = a * a; h1[q] = b * b; }
;                     __builtin_nontemporal_store(pack8(h0, h1), (u32x4*)(HID + (size_t)row * DFF + col)); } }
;     }
	v_fmamk_f32 v70, v70, 0x3a000000, v134
	v_mul_f32_e32 v71, 0x4b800000, v70
	v_cmp_gt_f32_e32 vcc, s0, v70
	s_nop 1
	v_cndmask_b32_e32 v70, v70, v71, vcc
	v_rsq_f32_e32 v70, v70
	s_nop 0
	v_mul_f32_e32 v64, 0x45800000, v70
	v_cndmask_b32_e32 v64, v70, v64, vcc
	v_pk_mul_f32 v[62:63], v[62:63], v[64:65] op_sel_hi:[1,0]
	v_pk_mul_f32 v[60:61], v[60:61], v[64:65] op_sel_hi:[1,0]
	v_pk_mul_f32 v[58:59], v[58:59], v[64:65] op_sel_hi:[1,0]
	v_pk_mul_f32 v[56:57], v[56:57], v[64:65] op_sel_hi:[1,0]
	v_pk_mul_f32 v[54:55], v[54:55], v[64:65] op_sel_hi:[1,0]
	v_pk_mul_f32 v[50:51], v[50:51], v[64:65] op_sel_hi:[1,0]
	v_pk_mul_f32 v[48:49], v[48:49], v[64:65] op_sel_hi:[1,0]
	v_pk_mul_f32 v[52:53], v[52:53], v[64:65] op_sel_hi:[1,0]
	v_max_f32_e32 v60, 0, v60
	v_max_f32_e32 v56, 0, v56
	v_max_f32_e32 v61, 0, v61
	v_max_f32_e32 v57, 0, v57
	v_max_f32_e32 v62, 0, v62
	v_max_f32_e32 v58, 0, v58
	v_max_f32_e32 v63, 0, v63
	v_max_f32_e32 v59, 0, v59
	v_max_f32_e32 v48, 0, v48
	v_max_f32_e32 v49, 0, v49
	v_max_f32_e32 v54, 0, v54
	v_max_f32_e32 v50, 0, v50
	v_max_f32_e32 v51, 0, v51
	v_max_f32_e32 v52, 0, v52
	v_max_f32_e32 v53, 0, v53
	v_max_f32_e32 v55, 0, v55
	v_mul_f32_e32 v60, v60, v60
	v_mul_f32_e32 v56, v56, v56
	v_mul_f32_e32 v61, v61, v61
	v_mul_f32_e32 v57, v57, v57
	v_mul_f32_e32 v62, v62, v62
	v_mul_f32_e32 v58, v58, v58
	v_mul_f32_e32 v63, v63, v63
	v_mul_f32_e32 v59, v59, v59
	v_mul_f32_e32 v64, v48, v48
	v_mul_f32_e32 v65, v49, v49
	v_mul_f32_e32 v54, v54, v54
	v_mul_f32_e32 v66, v50, v50
	v_mul_f32_e32 v67, v51, v51
	v_cvt_pk_bf16_f32 v48, v60, v61
	v_cvt_pk_bf16_f32 v49, v62, v63
	v_cvt_pk_bf16_f32 v50, v56, v57
	v_cvt_pk_bf16_f32 v51, v58, v59
	v_mul_f32_e32 v52, v52, v52
	v_mul_f32_e32 v53, v53, v53
	v_mul_f32_e32 v55, v55, v55
	global_store_dwordx4 v[68:69], v[48:51], off offset:-4096 nt
	s_nop 1
	v_cvt_pk_bf16_f32 v48, v52, v53
	v_cvt_pk_bf16_f32 v49, v54, v55
	v_cvt_pk_bf16_f32 v50, v64, v65
	v_cvt_pk_bf16_f32 v51, v66, v67
	global_load_dword v54, v[132:133], off offset:576
	v_add_u32_e32 v52, 0x90, v128
	global_store_dwordx4 v[68:69], v[48:51], off nt
	v_mov_b32_e32 v53, v129
	v_lshlrev_b64 v[52:53], 14, v[52:53]
	v_lshl_add_u64 v[52:53], s[4:5], 0, v[52:53]
	v_lshl_add_u64 v[52:53], v[52:53], 0, v[130:131]
	s_waitcnt vmcnt(1)
	v_fmamk_f32 v54, v54, 0x3a000000, v134
	v_mul_f32_e32 v55, 0x4b800000, v54
	v_cmp_gt_f32_e32 vcc, s0, v54
	s_nop 1
	v_cndmask_b32_e32 v54, v54, v55, vcc
	v_rsq_f32_e32 v54, v54
	s_nop 0
	v_mul_f32_e32 v48, 0x45800000, v54
	v_cndmask_b32_e32 v48, v54, v48, vcc
	v_pk_mul_f32 v[46:47], v[46:47], v[48:49] op_sel_hi:[1,0]
	v_pk_mul_f32 v[44:45], v[44:45], v[48:49] op_sel_hi:[1,0]
	v_pk_mul_f32 v[42:43], v[42:43], v[48:49] op_sel_hi:[1,0]
	v_pk_mul_f32 v[40:41], v[40:41], v[48:49] op_sel_hi:[1,0]
	v_pk_mul_f32 v[38:39], v[38:39], v[48:49] op_sel_hi:[1,0]
	v_pk_mul_f32 v[34:35], v[34:35], v[48:49] op_sel_hi:[1,0]
	v_pk_mul_f32 v[32:33], v[32:33], v[48:49] op_sel_hi:[1,0]
	v_pk_mul_f32 v[36:37], v[36:37], v[48:49] op_sel_hi:[1,0]
	v_max_f32_e32 v44, 0, v44
	v_max_f32_e32 v40, 0, v40
	v_max_f32_e32 v45, 0, v45
	v_max_f32_e32 v41, 0, v41
	v_max_f32_e32 v46, 0, v46
	v_max_f32_e32 v42, 0, v42
	v_max_f32_e32 v47, 0, v47
	v_max_f32_e32 v43, 0, v43
	v_max_f32_e32 v32, 0, v32
	v_max_f32_e32 v33, 0, v33
	v_max_f32_e32 v38, 0, v38
	v_max_f32_e32 v34, 0, v34
	v_max_f32_e32 v35, 0, v35
	v_max_f32_e32 v36, 0, v36
	v_max_f32_e32 v37, 0, v37
	v_max_f32_e32 v39, 0, v39
	v_mul_f32_e32 v44, v44, v44
	v_mul_f32_e32 v40, v40, v40
	v_mul_f32_e32 v45, v45, v45
	v_mul_f32_e32 v41, v41, v41
	v_mul_f32_e32 v46, v46, v46
	v_mul_f32_e32 v42, v42, v42
	v_mul_f32_e32 v47, v47, v47
	v_mul_f32_e32 v43, v43, v43
	v_mul_f32_e32 v48, v32, v32
	v_mul_f32_e32 v49, v33, v33
	v_mul_f32_e32 v38, v38, v38
	v_mul_f32_e32 v50, v34, v34
	v_mul_f32_e32 v51, v35, v35
	v_cvt_pk_bf16_f32 v32, v44, v45
	v_cvt_pk_bf16_f32 v33, v46, v47
	v_cvt_pk_bf16_f32 v34, v40, v41
	v_cvt_pk_bf16_f32 v35, v42, v43
	v_mul_f32_e32 v36, v36, v36
	v_mul_f32_e32 v37, v37, v37
	v_mul_f32_e32 v39, v39, v39
	global_store_dwordx4 v[52:53], v[32:35], off offset:-4096 nt
	s_nop 1
	v_cvt_pk_bf16_f32 v32, v36, v37
	v_cvt_pk_bf16_f32 v33, v38, v39
	v_cvt_pk_bf16_f32 v34, v48, v49
	v_cvt_pk_bf16_f32 v35, v50, v51
	global_load_dword v38, v[132:133], off offset:640
	v_add_u32_e32 v36, 0xa0, v128
	global_store_dwordx4 v[52:53], v[32:35], off nt
	v_mov_b32_e32 v37, v129
	v_lshlrev_b64 v[36:37], 14, v[36:37]
	v_lshl_add_u64 v[36:37], s[4:5], 0, v[36:37]
	v_lshl_add_u64 v[36:37], v[36:37], 0, v[130:131]
	v_add_u32_e32 v128, 0xb0, v128
	s_waitcnt vmcnt(1)
; __device__ __forceinline__ u32x4 pack8(const f32x4 a, const f32x4 b) { u32x4 w; w.x = cvt_pk_bf16(a[0], a[1]); w.y = cvt_pk_bf16(a[2], a[3]); w.z = cvt_pk_bf16(b[0], b[1]); w.w = cvt_pk_bf16(b[2], b[3]); return w; }
;     __device__ __forceinline__ void operator()(AccRef acc, const Unit& u, int wr, int wc, int fr, int fq) const {
; #pragma unroll
;         for (int ai = 0; ai < 2; ++ai)
; #pragma unroll
;             for (int m = 0; m < 4; ++m) { const int row = u.pm * 256 + ai * 128 + wr * 64 + m * 16 + fr;
;                 const float r2 = rsqrtf(ssq[row] * (1.0f / D) + EPS);
; #pragma unroll
;                 for (int bj = 0; bj < 2; ++bj) { const int col = u.pn * 256 + bj * 128 + wc * 32 + 8 * fq;
;                     f32x4 h0 = acc[ai][bj][m][0] * r2, h1 = acc[ai][bj][m][1] * r2;
; #pragma unroll
;                     for (int q = 0; q < 4; ++q) { const float a = fmaxf(h0[q], 0.f), b = fmaxf(h1[q], 0.f); h0[q] = a * a; h1[q] = b * b; }
;                     __builtin_nontemporal_store(pack8(h0, h1), (u32x4*)(HID + (size_t)row * DFF + col)); } }
;     }
	v_fmamk_f32 v38, v38, 0x3a000000, v134
	v_mul_f32_e32 v39, 0x4b800000, v38
	v_cmp_gt_f32_e32 vcc, s0, v38
	s_nop 1
	v_cndmask_b32_e32 v38, v38, v39, vcc
	v_rsq_f32_e32 v38, v38
	s_nop 0
	v_mul_f32_e32 v32, 0x45800000, v38
	v_cndmask_b32_e32 v32, v38, v32, vcc
	v_pk_mul_f32 v[30:31], v[30:31], v[32:33] op_sel_hi:[1,0]
	v_pk_mul_f32 v[28:29], v[28:29], v[32:33] op_sel_hi:[1,0]
	v_pk_mul_f32 v[26:27], v[26:27], v[32:33] op_sel_hi:[1,0]
	v_pk_mul_f32 v[24:25], v[24:25], v[32:33] op_sel_hi:[1,0]
	v_pk_mul_f32 v[22:23], v[22:23], v[32:33] op_sel_hi:[1,0]
	v_pk_mul_f32 v[18:19], v[18:19], v[32:33] op_sel_hi:[1,0]
	v_pk_mul_f32 v[16:17], v[16:17], v[32:33] op_sel_hi:[1,0]
	v_pk_mul_f32 v[20:21], v[20:21], v[32:33] op_sel_hi:[1,0]
	v_max_f32_e32 v28, 0, v28
	v_max_f32_e32 v24, 0, v24
	v_max_f32_e32 v29, 0, v29
	v_max_f32_e32 v25, 0, v25
	v_max_f32_e32 v30, 0, v30
	v_max_f32_e32 v26, 0, v26
	v_max_f32_e32 v31, 0, v31
	v_max_f32_e32 v27, 0, v27
	v_max_f32_e32 v16, 0, v16
	v_max_f32_e32 v17, 0, v17
	v_max_f32_e32 v22, 0, v22
	v_max_f32_e32 v18, 0, v18
	v_max_f32_e32 v19, 0, v19
	v_max_f32_e32 v20, 0, v20
	v_max_f32_e32 v21, 0, v21
	v_max_f32_e32 v23, 0, v23
	v_mul_f32_e32 v28, v28, v28
	v_mul_f32_e32 v24, v24, v24
	v_mul_f32_e32 v29, v29, v29
	v_mul_f32_e32 v25, v25, v25
	v_mul_f32_e32 v30, v30, v30
	v_mul_f32_e32 v26, v26, v26
	v_mul_f32_e32 v31, v31, v31
	v_mul_f32_e32 v27, v27, v27
	v_mul_f32_e32 v32, v16, v16
	v_mul_f32_e32 v33, v17, v17
	v_mul_f32_e32 v22, v22, v22
	v_mul_f32_e32 v34, v18, v18
	v_mul_f32_e32 v35, v19, v19
	v_cvt_pk_bf16_f32 v16, v28, v29
	v_cvt_pk_bf16_f32 v17, v30, v31
	v_cvt_pk_bf16_f32 v18, v24, v25
	v_cvt_pk_bf16_f32 v19, v26, v27
	v_mul_f32_e32 v20, v20, v20
	v_mul_f32_e32 v21, v21, v21
	v_mul_f32_e32 v23, v23, v23
	global_store_dwordx4 v[36:37], v[16:19], off offset:-4096 nt
	s_nop 1
	v_cvt_pk_bf16_f32 v16, v20, v21
	v_cvt_pk_bf16_f32 v17, v22, v23
	v_cvt_pk_bf16_f32 v18, v32, v33
	v_cvt_pk_bf16_f32 v19, v34, v35
	global_load_dword v22, v[132:133], off offset:704
	v_lshlrev_b64 v[20:21], 14, v[128:129]
	global_store_dwordx4 v[36:37], v[16:19], off nt
	v_lshl_add_u64 v[20:21], s[4:5], 0, v[20:21]
	v_lshl_add_u64 v[20:21], v[20:21], 0, v[130:131]
	s_waitcnt vmcnt(1)
	v_fmac_f32_e32 v134, 0x3a000000, v22
	v_mul_f32_e32 v22, 0x4b800000, v134
	v_cmp_gt_f32_e32 vcc, s0, v134
	s_nop 1
	v_cndmask_b32_e32 v22, v134, v22, vcc
	v_rsq_f32_e32 v22, v22
	s_nop 0
	v_mul_f32_e32 v16, 0x45800000, v22
	v_cndmask_b32_e32 v16, v22, v16, vcc
	v_pk_mul_f32 v[14:15], v[14:15], v[16:17] op_sel_hi:[1,0]
	v_pk_mul_f32 v[12:13], v[12:13], v[16:17] op_sel_hi:[1,0]
	v_pk_mul_f32 v[10:11], v[10:11], v[16:17] op_sel_hi:[1,0]
	v_pk_mul_f32 v[8:9], v[8:9], v[16:17] op_sel_hi:[1,0]
	v_pk_mul_f32 v[2:3], v[2:3], v[16:17] op_sel_hi:[1,0]
	v_pk_mul_f32 v[0:1], v[0:1], v[16:17] op_sel_hi:[1,0]
	v_pk_mul_f32 v[6:7], v[6:7], v[16:17] op_sel_hi:[1,0]
	v_pk_mul_f32 v[4:5], v[4:5], v[16:17] op_sel_hi:[1,0]
	v_max_f32_e32 v12, 0, v12
	v_max_f32_e32 v8, 0, v8
	v_max_f32_e32 v13, 0, v13
	v_max_f32_e32 v9, 0, v9
	v_max_f32_e32 v14, 0, v14
	v_max_f32_e32 v10, 0, v10
	v_max_f32_e32 v15, 0, v15
	v_max_f32_e32 v11, 0, v11
	v_max_f32_e32 v0, 0, v0
	v_max_f32_e32 v1, 0, v1
	v_max_f32_e32 v2, 0, v2
	v_max_f32_e32 v3, 0, v3
	v_max_f32_e32 v4, 0, v4
	v_max_f32_e32 v5, 0, v5
	v_max_f32_e32 v6, 0, v6
	v_max_f32_e32 v7, 0, v7
	v_mul_f32_e32 v12, v12, v12
	v_mul_f32_e32 v8, v8, v8
	v_mul_f32_e32 v13, v13, v13
	v_mul_f32_e32 v9, v9, v9
	v_mul_f32_e32 v14, v14, v14
	v_mul_f32_e32 v10, v10, v10
	v_mul_f32_e32 v15, v15, v15
	v_mul_f32_e32 v11, v11, v11
	v_mul_f32_e32 v16, v0, v0
	v_mul_f32_e32 v17, v1, v1
	v_mul_f32_e32 v18, v2, v2
	v_mul_f32_e32 v19, v3, v3
	v_cvt_pk_bf16_f32 v0, v12, v13
	v_cvt_pk_bf16_f32 v1, v14, v15
	v_cvt_pk_bf16_f32 v2, v8, v9
	v_cvt_pk_bf16_f32 v3, v10, v11
	v_mul_f32_e32 v4, v4, v4
	v_mul_f32_e32 v5, v5, v5
	v_mul_f32_e32 v6, v6, v6
	v_mul_f32_e32 v7, v7, v7
	global_store_dwordx4 v[20:21], v[0:3], off offset:-4096 nt
	s_nop 1
	v_cvt_pk_bf16_f32 v0, v4, v5
	v_cvt_pk_bf16_f32 v1, v6, v7
	v_cvt_pk_bf16_f32 v2, v16, v17
	v_cvt_pk_bf16_f32 v3, v18, v19
	global_store_dwordx4 v[20:21], v[0:3], off nt
	s_waitcnt vmcnt(0)
	s_barrier

; __device__ __forceinline__ u32x4 pack8(const f32x4 a, const f32x4 b) { u32x4 w; w.x = cvt_pk_bf16(a[0], a[1]); w.y = cvt_pk_bf16(a[2], a[3]); w.z = cvt_pk_bf16(b[0], b[1]); w.w = cvt_pk_bf16(b[2], b[3]); return w; }
;     __device__ __forceinline__ void operator()(AccRef acc, const Unit& u, int wr, int wc, int fr, int fq) const {
; #pragma unroll
;         for (int ai = 0; ai < 2; ++ai)
; #pragma unroll
;             for (int m = 0; m < 4; ++m) { const int row = u.pm * 256 + ai * 128 + wr * 64 + m * 16 + fr;
;                 const float r2 = rsqrtf(ssq[row] * (1.0f / D) + EPS);
; #pragma unroll
;                 for (int bj = 0; bj < 2; ++bj) { const int col = u.pn * 256 + bj * 128 + wc * 32 + 8 * fq;
;                     f32x4 h0 = acc[ai][bj][m][0] * r2, h1 = acc[ai][bj][m][1] * r2;
; #pragma unroll
;                     for (int q = 0; q < 4; ++q) { const float a = fmaxf(h0[q], 0.f), b = fmaxf(h1[q], 0.f); h0[q] = a * a; h1[q] = b * b; }
;                     __builtin_nontemporal_store(pack8(h0, h1), (u32x4*)(HID + (size_t)row * DFF + col)); } }
;     }
.LBB0_840:
	v_lshl_add_u32 v146, s24, 8, v137
	v_and_b32_e32 v146, -16, v146
	v_ashrrev_i32_e32 v147, 31, v146
	v_lshl_add_u64 v[150:151], v[146:147], 2, s[30:31]
	s_nop 0
	v_lshlrev_b64 v[160:161], 14, v[146:147]
	v_lshl_or_b32 v148, s2, 8, v154
	v_readlane_b32 s36, v242, 6
	v_lshrrev_b32_e32 v149, 5, v148
	v_lshlrev_b32_e32 v149, 10, v149
	v_readlane_b32 s37, v242, 7
	v_and_b32_e32 v148, 24, v148
	v_lshl_add_u32 v148, v148, 1, v149
	v_and_b32_e32 v149, 15, v136
	v_lshl_add_u32 v148, v149, 6, v148
	v_add_u32_e32 v148, 0x1000, v148
	v_mov_b32_e32 v149, 0
	s_nop 0
	v_fmamk_f32 v147, v230, 0x3a000000, v158
	v_mul_f32_e32 v159, 0x4b800000, v147
	v_cmp_gt_f32_e32 vcc, s50, v147
	v_lshl_add_u64 v[160:161], s[36:37], 0, v[160:161]
	v_lshl_add_u64 v[160:161], v[160:161], 0, v[148:149]
	v_cndmask_b32_e32 v147, v147, v159, vcc
	v_rsq_f32_e32 v147, v147
	s_nop 0
	v_mul_f32_e32 v159, 0x45800000, v147
	v_cndmask_b32_e32 v162, v147, v159, vcc
	v_pk_mul_f32 v[126:127], v[126:127], v[162:163] op_sel_hi:[1,0]
	v_pk_mul_f32 v[124:125], v[124:125], v[162:163] op_sel_hi:[1,0]
	v_pk_mul_f32 v[122:123], v[122:123], v[162:163] op_sel_hi:[1,0]
	v_pk_mul_f32 v[120:121], v[120:121], v[162:163] op_sel_hi:[1,0]
	v_pk_mul_f32 v[114:115], v[114:115], v[162:163] op_sel_hi:[1,0]
	v_pk_mul_f32 v[112:113], v[112:113], v[162:163] op_sel_hi:[1,0]
	v_pk_mul_f32 v[118:119], v[118:119], v[162:163] op_sel_hi:[1,0]
	v_pk_mul_f32 v[116:117], v[116:117], v[162:163] op_sel_hi:[1,0]
	v_max_f32_e32 v124, 0, v124
	v_max_f32_e32 v120, 0, v120
	v_max_f32_e32 v125, 0, v125
	v_max_f32_e32 v121, 0, v121
	v_max_f32_e32 v126, 0, v126
	v_max_f32_e32 v122, 0, v122
	v_max_f32_e32 v127, 0, v127
	v_max_f32_e32 v123, 0, v123
	v_max_f32_e32 v112, 0, v112
	v_max_f32_e32 v113, 0, v113
	v_max_f32_e32 v114, 0, v114
	v_max_f32_e32 v115, 0, v115
	v_max_f32_e32 v116, 0, v116
	v_max_f32_e32 v117, 0, v117
	v_max_f32_e32 v118, 0, v118
	v_max_f32_e32 v119, 0, v119
	v_mul_f32_e32 v124, v124, v124
	v_mul_f32_e32 v120, v120, v120
	v_mul_f32_e32 v125, v125, v125
	v_mul_f32_e32 v121, v121, v121
	v_mul_f32_e32 v126, v126, v126
	v_mul_f32_e32 v122, v122, v122
	v_mul_f32_e32 v127, v127, v127
	v_mul_f32_e32 v123, v123, v123
	v_mul_f32_e32 v147, v112, v112
	v_mul_f32_e32 v159, v113, v113
	v_mul_f32_e32 v162, v114, v114
	v_mul_f32_e32 v163, v115, v115
	v_cvt_pk_bf16_f32 v112, v124, v125
	v_cvt_pk_bf16_f32 v113, v126, v127
	v_cvt_pk_bf16_f32 v114, v120, v121
	v_cvt_pk_bf16_f32 v115, v122, v123
	v_mul_f32_e32 v116, v116, v116
	v_mul_f32_e32 v117, v117, v117
	v_mul_f32_e32 v118, v118, v118
	v_mul_f32_e32 v119, v119, v119
	global_store_dwordx4 v[160:161], v[112:115], off offset:-4096 nt
	s_nop 1
	v_cvt_pk_bf16_f32 v112, v116, v117
	v_cvt_pk_bf16_f32 v113, v118, v119
	v_cvt_pk_bf16_f32 v114, v147, v159
	v_cvt_pk_bf16_f32 v115, v162, v163
	global_store_dwordx4 v[160:161], v[112:115], off nt
	s_nop 0
	s_nop 0
	v_or_b32_e32 v112, 16, v146
	v_ashrrev_i32_e32 v113, 31, v112
	v_lshlrev_b64 v[112:113], 14, v[112:113]
	v_lshl_add_u64 v[112:113], s[36:37], 0, v[112:113]
	v_lshl_add_u64 v[112:113], v[112:113], 0, v[148:149]
	s_nop 0
	v_fmamk_f32 v114, v231, 0x3a000000, v158
	v_mul_f32_e32 v115, 0x4b800000, v114
	v_cmp_gt_f32_e32 vcc, s50, v114
	s_nop 1
	v_cndmask_b32_e32 v114, v114, v115, vcc
	v_rsq_f32_e32 v114, v114
	s_nop 0
	v_mul_f32_e32 v115, 0x45800000, v114
	v_cndmask_b32_e32 v114, v114, v115, vcc
	v_pk_mul_f32 v[110:111], v[110:111], v[114:115] op_sel_hi:[1,0]
	v_pk_mul_f32 v[108:109], v[108:109], v[114:115] op_sel_hi:[1,0]
	v_pk_mul_f32 v[106:107], v[106:107], v[114:115] op_sel_hi:[1,0]
	v_pk_mul_f32 v[104:105], v[104:105], v[114:115] op_sel_hi:[1,0]
	v_pk_mul_f32 v[98:99], v[98:99], v[114:115] op_sel_hi:[1,0]
	v_pk_mul_f32 v[96:97], v[96:97], v[114:115] op_sel_hi:[1,0]
	v_pk_mul_f32 v[102:103], v[102:103], v[114:115] op_sel_hi:[1,0]
	v_pk_mul_f32 v[100:101], v[100:101], v[114:115] op_sel_hi:[1,0]
	v_max_f32_e32 v108, 0, v108
	v_max_f32_e32 v104, 0, v104
	v_max_f32_e32 v109, 0, v109
	v_max_f32_e32 v105, 0, v105
	v_max_f32_e32 v110, 0, v110
	v_max_f32_e32 v106, 0, v106
	v_max_f32_e32 v111, 0, v111
	v_max_f32_e32 v107, 0, v107
	v_max_f32_e32 v96, 0, v96
	v_max_f32_e32 v97, 0, v97
	v_max_f32_e32 v98, 0, v98
	v_max_f32_e32 v99, 0, v99
	v_max_f32_e32 v100, 0, v100
	v_max_f32_e32 v101, 0, v101
	v_max_f32_e32 v102, 0, v102
	v_max_f32_e32 v103, 0, v103
	v_mul_f32_e32 v108, v108, v108
	v_mul_f32_e32 v104, v104, v104
	v_mul_f32_e32 v109, v109, v109
	v_mul_f32_e32 v105, v105, v105
	v_mul_f32_e32 v110, v110, v110
	v_mul_f32_e32 v106, v106, v106
	v_mul_f32_e32 v111, v111, v111
	v_mul_f32_e32 v107, v107, v107
	v_mul_f32_e32 v114, v96, v96
	v_mul_f32_e32 v115, v97, v97
	v_mul_f32_e32 v116, v98, v98
	v_mul_f32_e32 v117, v99, v99
	v_cvt_pk_bf16_f32 v96, v108, v109
	v_cvt_pk_bf16_f32 v97, v110, v111
	v_cvt_pk_bf16_f32 v98, v104, v105
	v_cvt_pk_bf16_f32 v99, v106, v107
	v_mul_f32_e32 v100, v100, v100
	v_mul_f32_e32 v101, v101, v101
	v_mul_f32_e32 v102, v102, v102
	v_mul_f32_e32 v103, v103, v103
	global_store_dwordx4 v[112:113], v[96:99], off offset:-4096 nt
	s_nop 1
	v_cvt_pk_bf16_f32 v96, v100, v101
	v_cvt_pk_bf16_f32 v97, v102, v103
	v_cvt_pk_bf16_f32 v98, v114, v115
	v_cvt_pk_bf16_f32 v99, v116, v117
	global_store_dwordx4 v[112:113], v[96:99], off nt
	s_nop 0
	s_nop 0
	v_or_b32_e32 v96, 32, v146
	v_ashrrev_i32_e32 v97, 31, v96
	v_lshlrev_b64 v[96:97], 14, v[96:97]
	v_lshl_add_u64 v[96:97], s[36:37], 0, v[96:97]
	v_lshl_add_u64 v[96:97], v[96:97], 0, v[148:149]
	s_nop 0
	v_fmamk_f32 v98, v232, 0x3a000000, v158
	v_mul_f32_e32 v99, 0x4b800000, v98
	v_cmp_gt_f32_e32 vcc, s50, v98
	s_nop 1
	v_cndmask_b32_e32 v98, v98, v99, vcc
	v_rsq_f32_e32 v98, v98
; __device__ __forceinline__ u32x4 pack8(const f32x4 a, const f32x4 b) { u32x4 w; w.x = cvt_pk_bf16(a[0], a[1]); w.y = cvt_pk_bf16(a[2], a[3]); w.z = cvt_pk_bf16(b[0], b[1]); w.w = cvt_pk_bf16(b[2], b[3]); return w; }
;     __device__ __forceinline__ void operator()(AccRef acc, const Unit& u, int wr, int wc, int fr, int fq) const {
; #pragma unroll
;         for (int ai = 0; ai < 2; ++ai)
; #pragma unroll
;             for (int m = 0; m < 4; ++m) { const int row = u.pm * 256 + ai * 128 + wr * 64 + m * 16 + fr;
;                 const float r2 = rsqrtf(ssq[row] * (1.0f / D) + EPS);
; #pragma unroll
;                 for (int bj = 0; bj < 2; ++bj) { const int col = u.pn * 256 + bj * 128 + wc * 32 + 8 * fq;
;                     f32x4 h0 = acc[ai][bj][m][0] * r2, h1 = acc[ai][bj][m][1] * r2;
; #pragma unroll
;                     for (int q = 0; q < 4; ++q) { const float a = fmaxf(h0[q], 0.f), b = fmaxf(h1[q], 0.f); h0[q] = a * a; h1[q] = b * b; }
;                     __builtin_nontemporal_store(pack8(h0, h1), (u32x4*)(HID + (size_t)row * DFF + col)); } }
;     }
	s_nop 0
	v_mul_f32_e32 v99, 0x45800000, v98
	v_cndmask_b32_e32 v98, v98, v99, vcc
	v_pk_mul_f32 v[94:95], v[94:95], v[98:99] op_sel_hi:[1,0]
	v_pk_mul_f32 v[92:93], v[92:93], v[98:99] op_sel_hi:[1,0]
	v_pk_mul_f32 v[90:91], v[90:91], v[98:99] op_sel_hi:[1,0]
	v_pk_mul_f32 v[88:89], v[88:89], v[98:99] op_sel_hi:[1,0]
	v_pk_mul_f32 v[82:83], v[82:83], v[98:99] op_sel_hi:[1,0]
	v_pk_mul_f32 v[80:81], v[80:81], v[98:99] op_sel_hi:[1,0]
	v_pk_mul_f32 v[86:87], v[86:87], v[98:99] op_sel_hi:[1,0]
	v_pk_mul_f32 v[84:85], v[84:85], v[98:99] op_sel_hi:[1,0]
	v_max_f32_e32 v92, 0, v92
	v_max_f32_e32 v88, 0, v88
	v_max_f32_e32 v93, 0, v93
	v_max_f32_e32 v89, 0, v89
	v_max_f32_e32 v94, 0, v94
	v_max_f32_e32 v90, 0, v90
	v_max_f32_e32 v95, 0, v95
	v_max_f32_e32 v91, 0, v91
	v_max_f32_e32 v80, 0, v80
	v_max_f32_e32 v81, 0, v81
	v_max_f32_e32 v82, 0, v82
	v_max_f32_e32 v83, 0, v83
	v_max_f32_e32 v84, 0, v84
	v_max_f32_e32 v85, 0, v85
	v_max_f32_e32 v86, 0, v86
	v_max_f32_e32 v87, 0, v87
	v_mul_f32_e32 v92, v92, v92
	v_mul_f32_e32 v88, v88, v88
	v_mul_f32_e32 v93, v93, v93
	v_mul_f32_e32 v89, v89, v89
	v_mul_f32_e32 v94, v94, v94
	v_mul_f32_e32 v90, v90, v90
	v_mul_f32_e32 v95, v95, v95
	v_mul_f32_e32 v91, v91, v91
	v_mul_f32_e32 v98, v80, v80
	v_mul_f32_e32 v99, v81, v81
	v_mul_f32_e32 v100, v82, v82
	v_mul_f32_e32 v101, v83, v83
	v_cvt_pk_bf16_f32 v80, v92, v93
	v_cvt_pk_bf16_f32 v81, v94, v95
	v_cvt_pk_bf16_f32 v82, v88, v89
	v_cvt_pk_bf16_f32 v83, v90, v91
	v_mul_f32_e32 v84, v84, v84
	v_mul_f32_e32 v85, v85, v85
	v_mul_f32_e32 v86, v86, v86
	v_mul_f32_e32 v87, v87, v87
	global_store_dwordx4 v[96:97], v[80:83], off offset:-4096 nt
	s_nop 1
	v_cvt_pk_bf16_f32 v80, v84, v85
	v_cvt_pk_bf16_f32 v81, v86, v87
	v_cvt_pk_bf16_f32 v82, v98, v99
	v_cvt_pk_bf16_f32 v83, v100, v101
	global_store_dwordx4 v[96:97], v[80:83], off nt
	s_nop 0
	s_nop 0
	v_or_b32_e32 v80, 48, v146
	v_ashrrev_i32_e32 v81, 31, v80
	v_lshlrev_b64 v[80:81], 14, v[80:81]
	v_lshl_add_u64 v[80:81], s[36:37], 0, v[80:81]
	v_lshl_add_u64 v[80:81], v[80:81], 0, v[148:149]
	s_nop 0
	v_fmamk_f32 v82, v233, 0x3a000000, v158
	v_mul_f32_e32 v83, 0x4b800000, v82
	v_cmp_gt_f32_e32 vcc, s50, v82
	s_nop 1
	v_cndmask_b32_e32 v82, v82, v83, vcc
	v_rsq_f32_e32 v82, v82
	s_nop 0
	v_mul_f32_e32 v83, 0x45800000, v82
	v_cndmask_b32_e32 v82, v82, v83, vcc
	v_pk_mul_f32 v[78:79], v[78:79], v[82:83] op_sel_hi:[1,0]
	v_pk_mul_f32 v[76:77], v[76:77], v[82:83] op_sel_hi:[1,0]
	v_pk_mul_f32 v[74:75], v[74:75], v[82:83] op_sel_hi:[1,0]
	v_pk_mul_f32 v[72:73], v[72:73], v[82:83] op_sel_hi:[1,0]
	v_pk_mul_f32 v[66:67], v[66:67], v[82:83] op_sel_hi:[1,0]
	v_pk_mul_f32 v[64:65], v[64:65], v[82:83] op_sel_hi:[1,0]
	v_pk_mul_f32 v[70:71], v[70:71], v[82:83] op_sel_hi:[1,0]
	v_pk_mul_f32 v[68:69], v[68:69], v[82:83] op_sel_hi:[1,0]
	v_max_f32_e32 v76, 0, v76
	v_max_f32_e32 v72, 0, v72
	v_max_f32_e32 v77, 0, v77
	v_max_f32_e32 v73, 0, v73
	v_max_f32_e32 v78, 0, v78
	v_max_f32_e32 v74, 0, v74
	v_max_f32_e32 v79, 0, v79
	v_max_f32_e32 v75, 0, v75
	v_max_f32_e32 v64, 0, v64
	v_max_f32_e32 v65, 0, v65
	v_max_f32_e32 v66, 0, v66
	v_max_f32_e32 v67, 0, v67
	v_max_f32_e32 v68, 0, v68
	v_max_f32_e32 v69, 0, v69
	v_max_f32_e32 v70, 0, v70
	v_max_f32_e32 v71, 0, v71
	v_mul_f32_e32 v76, v76, v76
	v_mul_f32_e32 v72, v72, v72
	v_mul_f32_e32 v77, v77, v77
	v_mul_f32_e32 v73, v73, v73
	v_mul_f32_e32 v78, v78, v78
	v_mul_f32_e32 v74, v74, v74
	v_mul_f32_e32 v79, v79, v79
	v_mul_f32_e32 v75, v75, v75
	v_mul_f32_e32 v82, v64, v64
	v_mul_f32_e32 v83, v65, v65
	v_mul_f32_e32 v84, v66, v66
	v_mul_f32_e32 v85, v67, v67
	v_cvt_pk_bf16_f32 v64, v76, v77
	v_cvt_pk_bf16_f32 v65, v78, v79
	v_cvt_pk_bf16_f32 v66, v72, v73
	v_cvt_pk_bf16_f32 v67, v74, v75
	v_mul_f32_e32 v68, v68, v68
	v_mul_f32_e32 v69, v69, v69
	v_mul_f32_e32 v70, v70, v70
	v_mul_f32_e32 v71, v71, v71
	global_store_dwordx4 v[80:81], v[64:67], off offset:-4096 nt
	s_nop 1
	v_cvt_pk_bf16_f32 v64, v68, v69
	v_cvt_pk_bf16_f32 v65, v70, v71
	v_cvt_pk_bf16_f32 v66, v82, v83
	v_cvt_pk_bf16_f32 v67, v84, v85
	global_store_dwordx4 v[80:81], v[64:67], off nt
	s_nop 0
	s_nop 0
	v_add_u32_e32 v64, 0x80, v146
	v_ashrrev_i32_e32 v65, 31, v64
	v_lshlrev_b64 v[64:65], 14, v[64:65]
	v_lshl_add_u64 v[64:65], s[36:37], 0, v[64:65]
	v_lshl_add_u64 v[64:65], v[64:65], 0, v[148:149]
	s_nop 0
	v_fmamk_f32 v66, v234, 0x3a000000, v158
	v_mul_f32_e32 v67, 0x4b800000, v66
	v_cmp_gt_f32_e32 vcc, s50, v66
	s_nop 1
	v_cndmask_b32_e32 v66, v66, v67, vcc
	v_rsq_f32_e32 v66, v66
	s_nop 0
	v_mul_f32_e32 v67, 0x45800000, v66
	v_cndmask_b32_e32 v66, v66, v67, vcc
	v_pk_mul_f32 v[62:63], v[62:63], v[66:67] op_sel_hi:[1,0]
	v_pk_mul_f32 v[60:61], v[60:61], v[66:67] op_sel_hi:[1,0]
	v_pk_mul_f32 v[58:59], v[58:59], v[66:67] op_sel_hi:[1,0]
	v_pk_mul_f32 v[56:57], v[56:57], v[66:67] op_sel_hi:[1,0]
	v_pk_mul_f32 v[50:51], v[50:51], v[66:67] op_sel_hi:[1,0]
	v_pk_mul_f32 v[48:49], v[48:49], v[66:67] op_sel_hi:[1,0]
	v_pk_mul_f32 v[54:55], v[54:55], v[66:67] op_sel_hi:[1,0]
	v_pk_mul_f32 v[52:53], v[52:53], v[66:67] op_sel_hi:[1,0]
	v_max_f32_e32 v60, 0, v60
	v_max_f32_e32 v56, 0, v56
	v_max_f32_e32 v61, 0, v61
	v_max_f32_e32 v57, 0, v57
	v_max_f32_e32 v62, 0, v62
	v_max_f32_e32 v58, 0, v58
	v_max_f32_e32 v63, 0, v63
	v_max_f32_e32 v59, 0, v59
	v_max_f32_e32 v48, 0, v48
	v_max_f32_e32 v49, 0, v49
	v_max_f32_e32 v50, 0, v50
	v_max_f32_e32 v51, 0, v51
	v_max_f32_e32 v52, 0, v52
	v_max_f32_e32 v53, 0, v53
	v_max_f32_e32 v54, 0, v54
	v_max_f32_e32 v55, 0, v55
	v_mul_f32_e32 v60, v60, v60
	v_mul_f32_e32 v56, v56, v56
	v_mul_f32_e32 v61, v61, v61
	v_mul_f32_e32 v57, v57, v57
	v_mul_f32_e32 v62, v62, v62
	v_mul_f32_e32 v58, v58, v58
; __device__ __forceinline__ u32x4 pack8(const f32x4 a, const f32x4 b) { u32x4 w; w.x = cvt_pk_bf16(a[0], a[1]); w.y = cvt_pk_bf16(a[2], a[3]); w.z = cvt_pk_bf16(b[0], b[1]); w.w = cvt_pk_bf16(b[2], b[3]); return w; }
;     __device__ __forceinline__ void operator()(AccRef acc, const Unit& u, int wr, int wc, int fr, int fq) const {
; #pragma unroll
;         for (int ai = 0; ai < 2; ++ai)
; #pragma unroll
;             for (int m = 0; m < 4; ++m) { const int row = u.pm * 256 + ai * 128 + wr * 64 + m * 16 + fr;
;                 const float r2 = rsqrtf(ssq[row] * (1.0f / D) + EPS);
; #pragma unroll
;                 for (int bj = 0; bj < 2; ++bj) { const int col = u.pn * 256 + bj * 128 + wc * 32 + 8 * fq;
;                     f32x4 h0 = acc[ai][bj][m][0] * r2, h1 = acc[ai][bj][m][1] * r2;
; #pragma unroll
;                     for (int q = 0; q < 4; ++q) { const float a = fmaxf(h0[q], 0.f), b = fmaxf(h1[q], 0.f); h0[q] = a * a; h1[q] = b * b; }
;                     __builtin_nontemporal_store(pack8(h0, h1), (u32x4*)(HID + (size_t)row * DFF + col)); } }
;     }
	v_mul_f32_e32 v63, v63, v63
	v_mul_f32_e32 v59, v59, v59
	v_mul_f32_e32 v66, v48, v48
	v_mul_f32_e32 v67, v49, v49
	v_mul_f32_e32 v68, v50, v50
	v_mul_f32_e32 v69, v51, v51
	v_cvt_pk_bf16_f32 v48, v60, v61
	v_cvt_pk_bf16_f32 v49, v62, v63
	v_cvt_pk_bf16_f32 v50, v56, v57
	v_cvt_pk_bf16_f32 v51, v58, v59
	v_mul_f32_e32 v52, v52, v52
	v_mul_f32_e32 v53, v53, v53
	v_mul_f32_e32 v54, v54, v54
	v_mul_f32_e32 v55, v55, v55
	global_store_dwordx4 v[64:65], v[48:51], off offset:-4096 nt
	s_nop 1
	v_cvt_pk_bf16_f32 v48, v52, v53
	v_cvt_pk_bf16_f32 v49, v54, v55
	v_cvt_pk_bf16_f32 v50, v66, v67
	v_cvt_pk_bf16_f32 v51, v68, v69
	global_store_dwordx4 v[64:65], v[48:51], off nt
	s_nop 0
	s_nop 0
	v_add_u32_e32 v48, 0x90, v146
	v_ashrrev_i32_e32 v49, 31, v48
	v_lshlrev_b64 v[48:49], 14, v[48:49]
	v_lshl_add_u64 v[48:49], s[36:37], 0, v[48:49]
	v_lshl_add_u64 v[48:49], v[48:49], 0, v[148:149]
	s_nop 0
	v_fmamk_f32 v50, v235, 0x3a000000, v158
	v_mul_f32_e32 v51, 0x4b800000, v50
	v_cmp_gt_f32_e32 vcc, s50, v50
	s_nop 1
	v_cndmask_b32_e32 v50, v50, v51, vcc
	v_rsq_f32_e32 v50, v50
	s_nop 0
	v_mul_f32_e32 v51, 0x45800000, v50
	v_cndmask_b32_e32 v50, v50, v51, vcc
	v_pk_mul_f32 v[46:47], v[46:47], v[50:51] op_sel_hi:[1,0]
	v_pk_mul_f32 v[44:45], v[44:45], v[50:51] op_sel_hi:[1,0]
	v_pk_mul_f32 v[42:43], v[42:43], v[50:51] op_sel_hi:[1,0]
	v_pk_mul_f32 v[40:41], v[40:41], v[50:51] op_sel_hi:[1,0]
	v_pk_mul_f32 v[34:35], v[34:35], v[50:51] op_sel_hi:[1,0]
	v_pk_mul_f32 v[32:33], v[32:33], v[50:51] op_sel_hi:[1,0]
	v_pk_mul_f32 v[38:39], v[38:39], v[50:51] op_sel_hi:[1,0]
	v_pk_mul_f32 v[36:37], v[36:37], v[50:51] op_sel_hi:[1,0]
	v_max_f32_e32 v44, 0, v44
	v_max_f32_e32 v40, 0, v40
	v_max_f32_e32 v45, 0, v45
	v_max_f32_e32 v41, 0, v41
	v_max_f32_e32 v46, 0, v46
	v_max_f32_e32 v42, 0, v42
	v_max_f32_e32 v47, 0, v47
	v_max_f32_e32 v43, 0, v43
	v_max_f32_e32 v32, 0, v32
	v_max_f32_e32 v33, 0, v33
	v_max_f32_e32 v34, 0, v34
	v_max_f32_e32 v35, 0, v35
	v_max_f32_e32 v36, 0, v36
	v_max_f32_e32 v37, 0, v37
	v_max_f32_e32 v38, 0, v38
	v_max_f32_e32 v39, 0, v39
	v_mul_f32_e32 v44, v44, v44
	v_mul_f32_e32 v40, v40, v40
	v_mul_f32_e32 v45, v45, v45
	v_mul_f32_e32 v41, v41, v41
	v_mul_f32_e32 v46, v46, v46
	v_mul_f32_e32 v42, v42, v42
	v_mul_f32_e32 v47, v47, v47
	v_mul_f32_e32 v43, v43, v43
	v_mul_f32_e32 v50, v32, v32
	v_mul_f32_e32 v51, v33, v33
	v_mul_f32_e32 v52, v34, v34
	v_mul_f32_e32 v53, v35, v35
	v_cvt_pk_bf16_f32 v32, v44, v45
	v_cvt_pk_bf16_f32 v33, v46, v47
	v_cvt_pk_bf16_f32 v34, v40, v41
	v_cvt_pk_bf16_f32 v35, v42, v43
	v_mul_f32_e32 v36, v36, v36
	v_mul_f32_e32 v37, v37, v37
	v_mul_f32_e32 v38, v38, v38
	v_mul_f32_e32 v39, v39, v39
	global_store_dwordx4 v[48:49], v[32:35], off offset:-4096 nt
	s_nop 1
	v_cvt_pk_bf16_f32 v32, v36, v37
	v_cvt_pk_bf16_f32 v33, v38, v39
	v_cvt_pk_bf16_f32 v34, v50, v51
	v_cvt_pk_bf16_f32 v35, v52, v53
	global_store_dwordx4 v[48:49], v[32:35], off nt
	s_nop 0
	s_nop 0
	v_add_u32_e32 v32, 0xa0, v146
	v_ashrrev_i32_e32 v33, 31, v32
	v_lshlrev_b64 v[32:33], 14, v[32:33]
	v_lshl_add_u64 v[32:33], s[36:37], 0, v[32:33]
	v_lshl_add_u64 v[32:33], v[32:33], 0, v[148:149]
	s_nop 0
	v_fmamk_f32 v34, v236, 0x3a000000, v158
	v_mul_f32_e32 v35, 0x4b800000, v34
	v_cmp_gt_f32_e32 vcc, s50, v34
	s_nop 1
	v_cndmask_b32_e32 v34, v34, v35, vcc
	v_rsq_f32_e32 v34, v34
	s_nop 0
	v_mul_f32_e32 v35, 0x45800000, v34
	v_cndmask_b32_e32 v34, v34, v35, vcc
	v_pk_mul_f32 v[30:31], v[30:31], v[34:35] op_sel_hi:[1,0]
	v_pk_mul_f32 v[28:29], v[28:29], v[34:35] op_sel_hi:[1,0]
	v_pk_mul_f32 v[26:27], v[26:27], v[34:35] op_sel_hi:[1,0]
	v_pk_mul_f32 v[24:25], v[24:25], v[34:35] op_sel_hi:[1,0]
	v_pk_mul_f32 v[18:19], v[18:19], v[34:35] op_sel_hi:[1,0]
	v_pk_mul_f32 v[16:17], v[16:17], v[34:35] op_sel_hi:[1,0]
; __device__ __forceinline__ u32x4 pack8(const f32x4 a, const f32x4 b) { u32x4 w; w.x = cvt_pk_bf16(a[0], a[1]); w.y = cvt_pk_bf16(a[2], a[3]); w.z = cvt_pk_bf16(b[0], b[1]); w.w = cvt_pk_bf16(b[2], b[3]); return w; }
; #define PG8_BAR __builtin_amdgcn_s_barrier()
; template <class Epi, class Sched>
; __device__ __forceinline__ void gemm_phase(LAS unsigned char* lds, const Gemm g, const Sched& S, const Epi& E) {
;     ...
;         }
;         if (wr == 0) PG8_BAR;
;         E(acc, cur, wr, wc, fr, fq);
;     __device__ __forceinline__ void operator()(AccRef acc, const Unit& u, int wr, int wc, int fr, int fq) const {
; #pragma unroll
;         for (int ai = 0; ai < 2; ++ai)
; #pragma unroll
;             for (int m = 0; m < 4; ++m) { const int row = u.pm * 256 + ai * 128 + wr * 64 + m * 16 + fr;
;                 const float r2 = rsqrtf(ssq[row] * (1.0f / D) + EPS);
; #pragma unroll
;                 for (int bj = 0; bj < 2; ++bj) { const int col = u.pn * 256 + bj * 128 + wc * 32 + 8 * fq;
;                     f32x4 h0 = acc[ai][bj][m][0] * r2, h1 = acc[ai][bj][m][1] * r2;
; #pragma unroll
;                     for (int q = 0; q < 4; ++q) { const float a = fmaxf(h0[q], 0.f), b = fmaxf(h1[q], 0.f); h0[q] = a * a; h1[q] = b * b; }
;                     __builtin_nontemporal_store(pack8(h0, h1), (u32x4*)(HID + (size_t)row * DFF + col)); } }
;     }
	v_pk_mul_f32 v[22:23], v[22:23], v[34:35] op_sel_hi:[1,0]
	v_pk_mul_f32 v[20:21], v[20:21], v[34:35] op_sel_hi:[1,0]
	v_max_f32_e32 v28, 0, v28
	v_max_f32_e32 v24, 0, v24
	v_max_f32_e32 v29, 0, v29
	v_max_f32_e32 v25, 0, v25
	v_max_f32_e32 v30, 0, v30
	v_max_f32_e32 v26, 0, v26
	v_max_f32_e32 v31, 0, v31
	v_max_f32_e32 v27, 0, v27
	v_max_f32_e32 v16, 0, v16
	v_max_f32_e32 v17, 0, v17
	v_max_f32_e32 v18, 0, v18
	v_max_f32_e32 v19, 0, v19
	v_max_f32_e32 v20, 0, v20
	v_max_f32_e32 v21, 0, v21
	v_max_f32_e32 v22, 0, v22
	v_max_f32_e32 v23, 0, v23
	v_mul_f32_e32 v28, v28, v28
	v_mul_f32_e32 v24, v24, v24
	v_mul_f32_e32 v29, v29, v29
	v_mul_f32_e32 v25, v25, v25
	v_mul_f32_e32 v30, v30, v30
	v_mul_f32_e32 v26, v26, v26
	v_mul_f32_e32 v31, v31, v31
	v_mul_f32_e32 v27, v27, v27
	v_mul_f32_e32 v34, v16, v16
	v_mul_f32_e32 v35, v17, v17
	v_mul_f32_e32 v36, v18, v18
	v_mul_f32_e32 v37, v19, v19
	v_cvt_pk_bf16_f32 v16, v28, v29
	v_cvt_pk_bf16_f32 v17, v30, v31
	v_cvt_pk_bf16_f32 v18, v24, v25
	v_cvt_pk_bf16_f32 v19, v26, v27
	v_mul_f32_e32 v20, v20, v20
	v_mul_f32_e32 v21, v21, v21
	v_mul_f32_e32 v22, v22, v22
	v_mul_f32_e32 v23, v23, v23
	global_store_dwordx4 v[32:33], v[16:19], off offset:-4096 nt
	s_andn2_b64 vcc, exec, s[0:1]
	s_nop 0
	v_cvt_pk_bf16_f32 v16, v20, v21
	v_cvt_pk_bf16_f32 v17, v22, v23
	v_cvt_pk_bf16_f32 v18, v34, v35
	v_cvt_pk_bf16_f32 v19, v36, v37
	global_store_dwordx4 v[32:33], v[16:19], off nt
	s_nop 0
	s_nop 0
	v_add_u32_e32 v16, 0xb0, v146
	v_ashrrev_i32_e32 v17, 31, v16
	v_lshlrev_b64 v[16:17], 14, v[16:17]
	v_lshl_add_u64 v[16:17], s[36:37], 0, v[16:17]
	v_lshl_add_u64 v[16:17], v[16:17], 0, v[148:149]
	s_nop 0
	v_fmamk_f32 v18, v237, 0x3a000000, v158
	v_mul_f32_e32 v19, 0x4b800000, v18
	v_cmp_gt_f32_e64 s[0:1], s50, v18
	s_nop 1
	v_cndmask_b32_e64 v18, v18, v19, s[0:1]
	v_rsq_f32_e32 v18, v18
	s_nop 0
	v_mul_f32_e32 v19, 0x45800000, v18
	v_cndmask_b32_e64 v18, v18, v19, s[0:1]
	v_pk_mul_f32 v[14:15], v[14:15], v[18:19] op_sel_hi:[1,0]
	v_pk_mul_f32 v[12:13], v[12:13], v[18:19] op_sel_hi:[1,0]
	v_pk_mul_f32 v[10:11], v[10:11], v[18:19] op_sel_hi:[1,0]
	v_pk_mul_f32 v[8:9], v[8:9], v[18:19] op_sel_hi:[1,0]
	v_pk_mul_f32 v[2:3], v[2:3], v[18:19] op_sel_hi:[1,0]
	v_pk_mul_f32 v[0:1], v[0:1], v[18:19] op_sel_hi:[1,0]
	v_pk_mul_f32 v[6:7], v[6:7], v[18:19] op_sel_hi:[1,0]
	v_pk_mul_f32 v[4:5], v[4:5], v[18:19] op_sel_hi:[1,0]
	v_max_f32_e32 v12, 0, v12
	v_max_f32_e32 v8, 0, v8
	v_max_f32_e32 v13, 0, v13
	v_max_f32_e32 v9, 0, v9
	v_max_f32_e32 v14, 0, v14
	v_max_f32_e32 v10, 0, v10
	v_max_f32_e32 v15, 0, v15
	v_max_f32_e32 v11, 0, v11
	v_max_f32_e32 v0, 0, v0
	v_max_f32_e32 v1, 0, v1
	v_max_f32_e32 v2, 0, v2
	v_max_f32_e32 v3, 0, v3
	v_max_f32_e32 v4, 0, v4
	v_max_f32_e32 v5, 0, v5
	v_max_f32_e32 v6, 0, v6
	v_max_f32_e32 v7, 0, v7
	v_mul_f32_e32 v12, v12, v12
	v_mul_f32_e32 v8, v8, v8
	v_mul_f32_e32 v13, v13, v13
	v_mul_f32_e32 v9, v9, v9
	v_mul_f32_e32 v14, v14, v14
	v_mul_f32_e32 v10, v10, v10
	v_mul_f32_e32 v15, v15, v15
	v_mul_f32_e32 v11, v11, v11
	v_mul_f32_e32 v18, v0, v0
	v_mul_f32_e32 v19, v1, v1
	v_mul_f32_e32 v20, v2, v2
	v_mul_f32_e32 v21, v3, v3
	v_cvt_pk_bf16_f32 v0, v12, v13
	v_cvt_pk_bf16_f32 v1, v14, v15
	v_cvt_pk_bf16_f32 v2, v8, v9
	v_cvt_pk_bf16_f32 v3, v10, v11
	s_mov_b64 s[0:1], -1
	v_mul_f32_e32 v4, v4, v4
	v_mul_f32_e32 v5, v5, v5
	v_mul_f32_e32 v6, v6, v6
	v_mul_f32_e32 v7, v7, v7
	global_store_dwordx4 v[16:17], v[0:3], off offset:-4096 nt
	s_nop 1
	v_cvt_pk_bf16_f32 v0, v4, v5
	v_cvt_pk_bf16_f32 v1, v6, v7
	v_cvt_pk_bf16_f32 v2, v18, v19
	v_cvt_pk_bf16_f32 v3, v20, v21
	global_store_dwordx4 v[16:17], v[0:3], off nt
	s_cbranch_vccnz .LBB0_829
	s_andn2_b64 vcc, exec, s[8:9]
	s_cbranch_vccnz .LBB0_828
	s_barrier
	s_branch .LBB0_828

;     __device__ bool next(int i, Unit& u) const { return at((long)i * G + c, u); }
;     __device__ bool next(int i, Unit& u) const { if (i > 0) return false; u.pm = pm; u.pn = pn; u.g = 0; u.nt = nt; u.k0 = 0; u.part = -1; return true; }
; #define PG8_STAGE(bufoff, gbase, voff) do { _Pragma("unroll") for (int _i = 0; _i < 2; ++_i) \
;         __builtin_amdgcn_global_load_lds((const unsigned*)((const char*)(gbase) + (voff)[_i]), (LAS unsigned*)(lds + (bufoff) + ldsw + _i * 8192), 16, 0, 0); } while (0)
; #define PG8_WAIT_V(n) asm volatile("s_waitcnt vmcnt(" #n ")" ::: "memory")
; template <class Epi, class Sched>
; __device__ __forceinline__ void gemm_phase(LAS unsigned char* lds, const Gemm g, const Sched& S, const Epi& E) {
;     const int tid = threadIdx.x, wid = __builtin_amdgcn_readfirstlane(tid >> 6), lane = tid & 63, wr = wid >> 2, wc = wid & 3, fr = lane & 15, fq = lane >> 4;
;     unsigned voffA[2], voffB[2];
; #pragma unroll
;     for (int i = 0; i < 2; ++i) { int R, C; stage_rc(tid * 16 + i * 8192, R, C); const int Rb = Epi::PERM ? ((R & ~31) + perm32(R & 31)) : R;
;         voffA[i] = (unsigned)(R * g.lda + C) * 2u; voffB[i] = (unsigned)(Rb * g.ldb + C) * 2u; }
;     const size_t kstep = (size_t)(BK * 2);
;     const size_t hstepA = (size_t)HALF * g.lda * 2, hstepB = (size_t)HALF * g.ldb * 2;
;     const unsigned ldsw = (unsigned)wid * 1024u;
;     const int aoff = lds_byte(wr * 64 + fr, fq * 8), boff = lds_byte(wc * 32 + fr, fq * 8);
;     ...
;     Unit cur, nxt; int ui = 0;
;     if (!S.next(0, cur)) return;
;     f32x4 acc[2][2][4][2];
; #pragma unroll
;     for (int a = 0; a < 2; ++a)
; #pragma unroll
;         for (int b = 0; b < 2; ++b)
; #pragma unroll
;             for (int m = 0; m < 4; ++m)
; #pragma unroll
;                 for (int n = 0; n < 2; ++n) acc[a][b][m][n] = (f32x4){0.f, 0.f, 0.f, 0.f};
;     bf16x8 At[4][2], B0[2][2], B1[2][2];
;     const char* cA = PG8_ABASE(cur); const char* cB = PG8_BBASE(cur);
;     PG8_STAGE(PG8_SB(0, 0), cB, voffB); PG8_STAGE(PG8_SB(0, 1), cB + hstepB, voffB); PG8_STAGE(PG8_SA(0, 0), cA, voffA); PG8_STAGE(PG8_SA(0, 1), cA + hstepA, voffA);
;     if (wr == 1) PG8_BAR;
;     PG8_WAIT_V(2); PG8_BAR;
;     PG8_STAGE(PG8_SB(1, 0), cB + kstep, voffB); PG8_STAGE(PG8_SA(1, 0), cA + kstep, voffA); PG8_STAGE(PG8_SB(1, 1), cB + hstepB + kstep, voffB);
;     PG8_WAIT_V(6); PG8_BAR;
.LBB0_905:
	s_andn2_b64 vcc, exec, s[6:7]
	s_cbranch_vccnz .LBB0_953
	v_lshrrev_b32_e32 v2, 1, v136
	v_lshrrev_b32_e32 v3, 5, v136
	v_and_b32_e32 v2, 24, v2
	v_and_b32_e32 v3, 4, v3
	v_bfe_u32 v4, v136, 2, 2
	v_lshlrev_b32_e32 v0, 4, v136
	s_waitcnt lgkmcnt(0)
	v_and_b32_e32 v1, 32, v136
	v_bfe_u32 v10, v136, 2, 4
	v_or3_b32 v2, v3, v4, v2
	v_lshrrev_b32_e32 v3, 3, v136
	s_movk_i32 s6, 0x70
	v_bitop3_b32 v8, v0, v1, 48 bitop3:0x6c
	v_and_b32_e32 v9, 64, v136
	v_and_or_b32 v4, v3, s6, v10
	s_movk_i32 s6, 0x60
	v_add_u32_e32 v11, 0x2000, v0
	v_or_b32_e32 v1, v8, v9
	v_and_or_b32 v3, v3, s6, v2
	v_lshrrev_b32_e32 v0, 7, v11
	s_movk_i32 s6, 0xf0
	v_lshl_or_b32 v156, v3, 14, v1
	v_and_or_b32 v3, v0, s6, v10
	s_movk_i32 s6, 0xe0
	v_and_or_b32 v0, v0, s6, v2
	s_lshr_b32 s6, s2, 6
	s_ashr_i32 s19, s18, 31
	s_lshr_b32 s5, s2, 8
	s_lshl_b32 s39, s6, 10
	s_lshl_b64 s[8:9], s[18:19], 22
	v_readlane_b32 s20, v242, 6
	v_readlane_b32 s21, v242, 7
	s_add_u32 s7, s20, s8
	s_addc_u32 s13, s21, s9
	s_ashr_i32 s17, s16, 31
	s_lshl_b64 s[8:9], s[16:17], 22
	s_add_u32 s8, s90, s8
	s_addc_u32 s9, s91, s9
	s_add_u32 s66, s8, s0
	s_addc_u32 s67, s9, s1
	s_add_i32 s17, s39, 0
	s_add_i32 m0, s17, 0x10000
	v_lshl_or_b32 v160, v0, 14, v1
	global_load_lds_dwordx4 v156, s[66:67]
	s_add_i32 m0, s17, 0x12000
	s_add_u32 s8, s66, 0x200000
	global_load_lds_dwordx4 v160, s[66:67]
	s_addc_u32 s9, s67, 0
	s_add_i32 m0, s17, 0x14000
	v_lshl_or_b32 v154, v4, 14, v1
	v_and_b32_e32 v240, 0x1c0000, v154
	v_bfe_u32 v241, v154, 14, 4
	v_lshl_or_b32 v240, v241, 6, v240
	v_and_b32_e32 v241, 64, v154
	v_lshl_or_b32 v240, v241, 4, v240
	v_and_or_b32 v154, v154, 63, v240
	global_load_lds_dwordx4 v156, s[8:9]
	s_add_i32 m0, s17, 0x16000
	v_lshl_or_b32 v158, v3, 14, v1
	v_and_b32_e32 v240, 0x1c0000, v158
	v_bfe_u32 v241, v158, 14, 4
	v_lshl_or_b32 v240, v241, 6, v240
	v_and_b32_e32 v241, 64, v158
	v_lshl_or_b32 v240, v241, 4, v240
	v_and_or_b32 v158, v158, 63, v240
	global_load_lds_dwordx4 v160, s[8:9]
	s_lshl_b64 s[100:101], s[0:1], 4
	s_add_u32 s8, s7, s100
	s_addc_u32 s9, s13, s101
	s_add_i32 s72, s17, 0x2000
	s_mov_b32 m0, s17
	s_add_u32 s0, s8, 0x200000
	global_load_lds_dwordx4 v154, s[8:9]
	s_mov_b32 m0, s72
	s_addc_u32 s1, s9, 0
	s_add_i32 s73, s17, 0x4000
	global_load_lds_dwordx4 v158, s[8:9]
	s_mov_b32 m0, s73
	s_add_i32 s76, s17, 0x6000
	global_load_lds_dwordx4 v154, s[0:1]
	s_mov_b32 m0, s76
	v_mov_b32_e32 v163, 0
	global_load_lds_dwordx4 v158, s[0:1]
	v_mov_b32_e32 v157, v163
	v_mov_b32_e32 v161, v163
	v_mov_b32_e32 v155, v163
	v_mov_b32_e32 v159, v163
	s_cmp_eq_u32 s5, 1
	s_mov_b32 s75, s87
	s_mov_b32 s13, 0
	v_lshl_add_u64 v[6:7], s[66:67], 0, v[156:157]
	v_lshl_add_u64 v[4:5], s[66:67], 0, v[160:161]
	v_lshl_add_u64 v[0:1], s[8:9], 0, v[154:155]
	s_cselect_b64 s[20:21], -1, 0
	s_cmp_lg_u32 s5, 1
	v_lshl_add_u64 v[2:3], s[8:9], 0, v[158:159]
	s_cbranch_scc1 .LBB0_908
	s_barrier
.LBB0_908:
	s_lshl_b32 s0, s6, 5
	s_and_b32 s19, s0, 0x60
	s_lshl_b32 s7, s5, 13
	s_lshl_b32 s6, s19, 7
	s_add_u32 s22, s30, 0xc8000
	s_addc_u32 s23, s31, 0
	s_add_u32 s77, s30, 0xea000
	s_mov_b64 s[24:25], 0x80
	s_mov_b64 s[98:99], 0x800
	s_addc_u32 s78, s31, 0
	s_add_i32 m0, s17, 0x18000
	v_lshl_add_u64 v[6:7], v[6:7], 0, s[24:25]
	s_waitcnt vmcnt(2)
	s_barrier
	global_load_lds_dwordx4 v[6:7], off
	v_lshl_add_u64 v[4:5], v[4:5], 0, s[24:25]
	s_add_i32 m0, s17, 0x1a000
	s_add_i32 s79, s17, 0x8000
	s_add_i32 s80, s17, 0xa000
	global_load_lds_dwordx4 v[4:5], off
	v_lshl_add_u64 v[0:1], v[0:1], 0, s[98:99]
	s_mov_b32 m0, s79
	s_add_u32 s0, s66, 0x200080
	global_load_lds_dwordx4 v[0:1], off
	v_lshl_add_u64 v[0:1], v[2:3], 0, s[98:99]
	s_mov_b32 m0, s80
	s_addc_u32 s1, s67, 0
	global_load_lds_dwordx4 v[0:1], off
	s_add_i32 m0, s17, 0x1c000
	v_lshl_add_u64 v[0:1], s[0:1], 0, v[156:157]
	global_load_lds_dwordx4 v[0:1], off
	v_lshl_add_u64 v[0:1], s[0:1], 0, v[160:161]
	s_add_i32 m0, s17, 0x1e000
	v_bfe_u32 v2, v136, 4, 2
	global_load_lds_dwordx4 v[0:1], off
	v_and_b32_e32 v1, 15, v136
	v_lshlrev_b32_e32 v3, 4, v2
	v_lshlrev_b32_e32 v5, 2, v136
	v_lshlrev_b32_e32 v6, 6, v136
	s_movk_i32 s0, 0x3c0
	v_lshl_or_b32 v164, s5, 6, v1
	v_lshl_or_b32 v4, v1, 6, v3
	v_and_b32_e32 v5, 32, v5
	v_and_or_b32 v3, v6, s0, v3
	v_or_b32_e32 v1, v2, v1
	v_bitop3_b32 v4, v4, s7, v5 bitop3:0xde
	v_bitop3_b32 v153, s6, v3, v5 bitop3:0xf6
	v_cmp_eq_u32_e64 s[6:7], 0, v1
	v_lshlrev_b32_e32 v1, 11, v136
	v_lshlrev_b32_e32 v0, 3, v2
	v_cmp_eq_u32_e64 s[0:1], 0, v2
	v_and_b32_e32 v1, 0x1c0000, v1
	v_lshlrev_b32_e32 v2, 14, v10
	v_or3_b32 v1, v8, v1, v2
	v_add_u32_e32 v168, v1, v9
	v_and_b32_e32 v240, 0x1c0000, v168
	v_bfe_u32 v241, v168, 14, 4
	v_lshl_or_b32 v240, v241, 6, v240
	v_and_b32_e32 v241, 64, v168
	v_lshl_or_b32 v240, v241, 4, v240
	v_and_or_b32 v168, v168, 63, v240
	v_lshlrev_b32_e32 v1, 7, v11
	s_waitcnt vmcnt(6)
	s_cmpk_lt_u32 s2, 0x100
	v_mov_b32_e32 v165, v163
	v_and_b32_e32 v1, 0x3c0000, v1
	s_cselect_b64 s[36:37], -1, 0
	v_lshlrev_b64 v[166:167], 13, v[164:165]
	v_or_b32_e32 v165, s19, v0
	v_or3_b32 v1, v8, v1, v2
	s_add_i32 s81, 0, 0x10000
	s_add_i32 s82, 0, 0x14000
	v_lshlrev_b32_e32 v162, 2, v0
	s_mov_b32 s42, 0xf0060000
	s_mov_b32 s44, 0xf0100000
	s_mov_b32 s48, 0xf0120000
	s_mov_b32 s50, 0xf0140000
	s_mov_b32 s52, 0xf0160000
	v_mbcnt_lo_u32_b32 v0, -1, 0
	v_mov_b32_e32 v169, v163
	v_add_u32_e32 v170, v1, v9
	v_and_b32_e32 v240, 0x1c0000, v170
	v_bfe_u32 v241, v170, 14, 4
	v_lshl_or_b32 v240, v241, 6, v240
	v_and_b32_e32 v241, 64, v170
	v_lshl_or_b32 v240, v241, 4, v240
	v_and_or_b32 v170, v170, 63, v240
	v_mov_b32_e32 v171, v163
	v_add_u32_e32 v208, s81, v153
	v_add_u32_e32 v209, s82, v153
	v_add_u32_e32 v210, 0, v4
	s_mov_b32 s38, 0x3a000000
	s_mov_b32 s83, 0x800000
	s_lshl_b32 s40, s19, 2
	s_mov_b32 s84, 0xf0040000
	s_mov_b32 s43, -1
	s_mov_b32 s85, 0xf0060000
	s_mov_b32 s45, -1
	s_mov_b32 s86, 0xf0100000
	s_mov_b32 s49, -1
	s_mov_b32 s33, 0xf0120000
	s_mov_b32 s51, -1
	s_mov_b32 s53, -1
	v_mbcnt_hi_u32_b32 v211, -1, v0
	s_mov_b32 s87, s13
	s_barrier
	s_branch .LBB0_911

;     __device__ bool next(int i, Unit& u) const { return at((long)i * G + c, u); }
;     __device__ bool next(int i, Unit& u) const { if (i > 0) return false; u.pm = pm; u.pn = pn; u.g = 0; u.nt = nt; u.k0 = 0; u.part = -1; return true; }
; #define PG8_STAGE(bufoff, gbase, voff) do { _Pragma("unroll") for (int _i = 0; _i < 2; ++_i) \
;         __builtin_amdgcn_global_load_lds((const unsigned*)((const char*)(gbase) + (voff)[_i]), (LAS unsigned*)(lds + (bufoff) + ldsw + _i * 8192), 16, 0, 0); } while (0)
; #define PG8_LDA(dst, b, h) do { _Pragma("unroll") for (int m = 0; m < 4; ++m) _Pragma("unroll") for (int k = 0; k < 2; ++k) dst[m][k] = *(const LAS bf16x8*)(lds + PG8_SA(b, h) + aoff + m * 2048 + k * 1024); } while (0)
; #define PG8_LDB(dst, b, h) do { _Pragma("unroll") for (int n = 0; n < 2; ++n) _Pragma("unroll") for (int k = 0; k < 2; ++k) dst[n][k] = *(const LAS bf16x8*)(lds + PG8_SB(b, h) + boff + n * 2048 + k * 1024); } while (0)
; #define PG8_WAIT_V(n) asm volatile("s_waitcnt vmcnt(" #n ")" ::: "memory")
; #define PG8_WAIT_L(n) asm volatile("s_waitcnt lgkmcnt(" #n ")" ::: "memory")
; #define PG8_BAR __builtin_amdgcn_s_barrier()
; template <class Epi, class Sched>
; __device__ __forceinline__ void gemm_phase(LAS unsigned char* lds, const Gemm g, const Sched& S, const Epi& E) {
;     ...
;         const bool has_next = S.next(ui + 1, nxt);
;         const char* nA = has_next ? PG8_ABASE(nxt) : cA; const char* nB = has_next ? PG8_BBASE(nxt) : cB;
;         const int nt = cur.nt;
;         for (int t = 0; t < nt; t += 2) {
;             const bool last = (t == nt - 2);
;             const char* a1 = cA + (size_t)(t + 1) * kstep;
;             const char* a2 = last ? nA : cA + (size_t)(t + 2) * kstep; const char* b2 = last ? nB : cB + (size_t)(t + 2) * kstep;
;             const char* a3 = a2 + kstep; const char* b3 = b2 + kstep;
;             PG8_LDB(B0, 0, 0); PG8_LDB(B1, 0, 1); PG8_SCHED; PG8_LDA(At, 0, 0); PG8_STAGE(PG8_SA(1, 1), a1 + hstepA, voffA);
;             PG8_WAIT_V(8); PG8_WAIT_L(0); PG8_BAR; PG8_MMA(0, 0, At, B0); PG8_MMA(0, 1, At, B1); PG8_BAR; PG8_SCHED;
;     ...
; #pragma unroll
;         for (int a = 0; a < 2; ++a)
; #pragma unroll
;             for (int b = 0; b < 2; ++b)
; #pragma unroll
;                 for (int m = 0; m < 4; ++m)
; #pragma unroll
;                     for (int n = 0; n < 2; ++n) acc[a][b][m][n] = (f32x4){0.f, 0.f, 0.f, 0.f};
.LBB0_916:
	s_ashr_i32 s55, s54, 31
	s_ashr_i32 s57, s56, 31
	s_lshl_b64 s[34:35], s[56:57], 7
	s_lshl_b64 s[46:47], s[54:55], 22
	v_readlane_b32 s62, v242, 6
	v_readlane_b32 s63, v242, 7
	s_add_u32 s2, s62, s46
	s_addc_u32 s5, s63, s47
	s_lshl_b64 s[100:101], s[56:57], 11
	s_add_u32 s62, s2, s100
	s_addc_u32 s63, s5, s101
	s_and_b64 s[46:47], s[60:61], exec
	s_cselect_b32 s2, s63, s9
	s_cselect_b32 s5, s62, s8
	s_ashr_i32 s59, s58, 31
	s_lshl_b64 s[46:47], s[58:59], 22
	s_add_u32 s19, s90, s46
	s_addc_u32 s41, s91, s47
	s_add_u32 s64, s19, s34
	s_addc_u32 s65, s41, s35
	s_and_b64 s[34:35], s[60:61], exec
	s_cselect_b32 s19, s65, s67
	s_cselect_b32 s34, s64, s66
	s_add_i32 s35, s4, -2
	s_add_u32 s8, s8, 0x200800
	s_addc_u32 s9, s9, 0
	s_add_u32 s41, s66, 0x100
	v_mov_b32_e32 v0, 0
	s_mov_b64 s[92:93], s[90:91]
	s_addc_u32 s46, s67, 0
	s_mov_b32 s47, 0
	v_mov_b32_e32 v1, v0
	v_mov_b32_e32 v2, v0
	v_mov_b32_e32 v3, v0
	v_mov_b32_e32 v4, v0
	v_mov_b32_e32 v5, v0
	v_mov_b32_e32 v6, v0
	v_mov_b32_e32 v7, v0
	v_mov_b32_e32 v8, v0
	v_mov_b32_e32 v9, v0
	v_mov_b32_e32 v10, v0
	v_mov_b32_e32 v11, v0
	v_mov_b32_e32 v12, v0
	v_mov_b32_e32 v13, v0
	v_mov_b32_e32 v14, v0
	v_mov_b32_e32 v15, v0
	v_mov_b32_e32 v20, v0
	v_mov_b32_e32 v21, v0
	v_mov_b32_e32 v22, v0
	v_mov_b32_e32 v23, v0
	v_mov_b32_e32 v28, v0
	v_mov_b32_e32 v29, v0
	v_mov_b32_e32 v30, v0
	v_mov_b32_e32 v31, v0
	v_mov_b32_e32 v36, v0
	v_mov_b32_e32 v37, v0
	v_mov_b32_e32 v38, v0
	v_mov_b32_e32 v39, v0
	v_mov_b32_e32 v44, v0
	v_mov_b32_e32 v45, v0
	v_mov_b32_e32 v46, v0
	v_mov_b32_e32 v47, v0
	v_mov_b32_e32 v16, v0
	v_mov_b32_e32 v17, v0
	v_mov_b32_e32 v18, v0
	v_mov_b32_e32 v19, v0
	s_waitcnt vmcnt(0)
	v_mov_b32_e32 v24, v0
	v_mov_b32_e32 v25, v0
	v_mov_b32_e32 v26, v0
	v_mov_b32_e32 v27, v0
	v_mov_b32_e32 v32, v0
	v_mov_b32_e32 v33, v0
	v_mov_b32_e32 v34, v0
	v_mov_b32_e32 v35, v0
	v_mov_b32_e32 v40, v0
	v_mov_b32_e32 v41, v0
	v_mov_b32_e32 v42, v0
	v_mov_b32_e32 v43, v0
	v_mov_b32_e32 v48, v0
	v_mov_b32_e32 v49, v0
	v_mov_b32_e32 v50, v0
	v_mov_b32_e32 v51, v0
	v_mov_b32_e32 v52, v0
	v_mov_b32_e32 v53, v0
	v_mov_b32_e32 v54, v0
	v_mov_b32_e32 v55, v0
	v_mov_b32_e32 v56, v0
	v_mov_b32_e32 v57, v0
	v_mov_b32_e32 v58, v0
	v_mov_b32_e32 v59, v0
	v_mov_b32_e32 v60, v0
	v_mov_b32_e32 v61, v0
	v_mov_b32_e32 v62, v0
	v_mov_b32_e32 v63, v0
	v_mov_b32_e32 v64, v0
	v_mov_b32_e32 v65, v0
	v_mov_b32_e32 v66, v0
	v_mov_b32_e32 v67, v0
	v_mov_b32_e32 v68, v0
	v_mov_b32_e32 v69, v0
	v_mov_b32_e32 v70, v0
	v_mov_b32_e32 v71, v0
	v_mov_b32_e32 v72, v0
	v_mov_b32_e32 v73, v0
	v_mov_b32_e32 v74, v0
	v_mov_b32_e32 v75, v0
	v_mov_b32_e32 v76, v0
	v_mov_b32_e32 v77, v0
	v_mov_b32_e32 v78, v0
	v_mov_b32_e32 v79, v0
	v_mov_b32_e32 v84, v0
	v_mov_b32_e32 v85, v0
	v_mov_b32_e32 v86, v0
	v_mov_b32_e32 v87, v0
	v_mov_b32_e32 v92, v0
	v_mov_b32_e32 v93, v0
	v_mov_b32_e32 v94, v0
	v_mov_b32_e32 v95, v0
	v_mov_b32_e32 v100, v0
	v_mov_b32_e32 v101, v0
	v_mov_b32_e32 v102, v0
	v_mov_b32_e32 v103, v0
	v_mov_b32_e32 v108, v0
	v_mov_b32_e32 v109, v0
	v_mov_b32_e32 v110, v0
	v_mov_b32_e32 v111, v0
	v_mov_b32_e32 v80, v0
	v_mov_b32_e32 v81, v0
	v_mov_b32_e32 v82, v0
	v_mov_b32_e32 v83, v0
	v_mov_b32_e32 v88, v0
	v_mov_b32_e32 v89, v0
	v_mov_b32_e32 v90, v0
	v_mov_b32_e32 v91, v0
	v_mov_b32_e32 v96, v0
	v_mov_b32_e32 v97, v0
	v_mov_b32_e32 v98, v0
	v_mov_b32_e32 v99, v0
	v_mov_b32_e32 v104, v0
	v_mov_b32_e32 v105, v0
	v_mov_b32_e32 v106, v0
	v_mov_b32_e32 v107, v0
	v_mov_b32_e32 v112, v0
	v_mov_b32_e32 v113, v0
	v_mov_b32_e32 v114, v0
	v_mov_b32_e32 v115, v0
	v_mov_b32_e32 v116, v0
	v_mov_b32_e32 v117, v0
	v_mov_b32_e32 v118, v0
	v_mov_b32_e32 v119, v0
	v_mov_b32_e32 v120, v0
	v_mov_b32_e32 v121, v0
	v_mov_b32_e32 v122, v0
	v_mov_b32_e32 v123, v0
	v_mov_b32_e32 v124, v0
	v_mov_b32_e32 v125, v0
	v_mov_b32_e32 v126, v0
	v_mov_b32_e32 v127, v0
.LBB0_917:
	ds_read_b128 v[128:131], v208
	ds_read_b128 v[132:135], v208 offset:1024
	ds_read_b128 v[136:139], v208 offset:2048
	ds_read_b128 v[140:143], v208 offset:3072
	ds_read_b128 v[144:147], v209
	ds_read_b128 v[148:151], v209 offset:1024
	ds_read_b128 v[172:175], v209 offset:2048
	ds_read_b128 v[176:179], v209 offset:3072
	s_add_i32 s55, s47, 2
	s_add_u32 s57, s8, 0xffe00800
	s_addc_u32 s59, s9, -1
	s_cmp_eq_u32 s35, s47
	s_cselect_b32 s71, s2, s59
	s_cselect_b32 s70, s5, s57
	s_cselect_b32 s67, s19, s46
	s_cselect_b32 s66, s34, s41
	v_lshl_add_u64 v[216:217], s[8:9], 0, v[168:169]
	s_add_i32 m0, s17, 0xc000
	ds_read_b128 v[180:183], v210
	ds_read_b128 v[184:187], v210 offset:1024
	ds_read_b128 v[188:191], v210 offset:2048
	ds_read_b128 v[192:195], v210 offset:3072
	ds_read_b128 v[196:199], v210 offset:4096
	ds_read_b128 v[200:203], v210 offset:5120
	ds_read_b128 v[204:207], v210 offset:6144
	ds_read_b128 v[212:215], v210 offset:7168
	global_load_lds_dwordx4 v[216:217], off
	v_lshl_add_u64 v[216:217], s[8:9], 0, v[170:171]
	s_add_i32 m0, s17, 0xe000
	s_nop 0
	global_load_lds_dwordx4 v[216:217], off
	s_waitcnt vmcnt(8)
	s_waitcnt lgkmcnt(0)
	s_barrier
; #define PG8_STAGE(bufoff, gbase, voff) do { _Pragma("unroll") for (int _i = 0; _i < 2; ++_i) \
;         __builtin_amdgcn_global_load_lds((const unsigned*)((const char*)(gbase) + (voff)[_i]), (LAS unsigned*)(lds + (bufoff) + ldsw + _i * 8192), 16, 0, 0); } while (0)
; #define PG8_LDA(dst, b, h) do { _Pragma("unroll") for (int m = 0; m < 4; ++m) _Pragma("unroll") for (int k = 0; k < 2; ++k) dst[m][k] = *(const LAS bf16x8*)(lds + PG8_SA(b, h) + aoff + m * 2048 + k * 1024); } while (0)
; #define PG8_LDB(dst, b, h) do { _Pragma("unroll") for (int n = 0; n < 2; ++n) _Pragma("unroll") for (int k = 0; k < 2; ++k) dst[n][k] = *(const LAS bf16x8*)(lds + PG8_SB(b, h) + boff + n * 2048 + k * 1024); } while (0)
; #define PG8_MMA(ai, bj, At, Bt) do { __builtin_amdgcn_s_setprio(1); _Pragma("unroll") for (int m = 0; m < 4; ++m) _Pragma("unroll") for (int n = 0; n < 2; ++n) _Pragma("unroll") for (int k = 0; k < 2; ++k) \
;         acc[ai][bj][m][n] = __builtin_amdgcn_mfma_f32_16x16x32_bf16(Bt[n][k], At[m][k], acc[ai][bj][m][n], 0, 0, 0); __builtin_amdgcn_s_setprio(0); } while (0)
; #define PG8_WAIT_V(n) asm volatile("s_waitcnt vmcnt(" #n ")" ::: "memory")
; #define PG8_WAIT_L(n) asm volatile("s_waitcnt lgkmcnt(" #n ")" ::: "memory")
; #define PG8_BAR __builtin_amdgcn_s_barrier()
; #define PG8_SCHED __builtin_amdgcn_sched_barrier(0)
; template <class Epi, class Sched>
; __device__ __forceinline__ void gemm_phase(LAS unsigned char* lds, const Gemm g, const Sched& S, const Epi& E) {
;     ...
;             PG8_LDB(B0, 0, 0); PG8_LDB(B1, 0, 1); PG8_SCHED; PG8_LDA(At, 0, 0); PG8_STAGE(PG8_SA(1, 1), a1 + hstepA, voffA);
;             PG8_WAIT_V(8); PG8_WAIT_L(0); PG8_BAR; PG8_MMA(0, 0, At, B0); PG8_MMA(0, 1, At, B1); PG8_BAR; PG8_SCHED;
;             PG8_LDA(At, 0, 1); PG8_STAGE(PG8_SB(0, 0), b2, voffB); PG8_STAGE(PG8_SB(0, 1), b2 + hstepB, voffB); PG8_STAGE(PG8_SA(0, 0), a2, voffA);
;             PG8_WAIT_V(8); PG8_WAIT_L(0); PG8_BAR; PG8_MMA(1, 0, At, B0); PG8_MMA(1, 1, At, B1); PG8_BAR; PG8_SCHED;
	s_setprio 1
	s_waitcnt lgkmcnt(0)
	v_mfma_f32_16x16x32_bf16 v[124:127], v[128:131], v[180:183], v[124:127]
	v_mfma_f32_16x16x32_bf16 v[120:123], v[136:139], v[180:183], v[120:123]
	v_mfma_f32_16x16x32_bf16 v[116:119], v[128:131], v[188:191], v[116:119]
	v_mfma_f32_16x16x32_bf16 v[112:115], v[136:139], v[188:191], v[112:115]
	v_mfma_f32_16x16x32_bf16 v[104:107], v[128:131], v[196:199], v[104:107]
	v_mfma_f32_16x16x32_bf16 v[96:99], v[136:139], v[196:199], v[96:99]
	v_mfma_f32_16x16x32_bf16 v[88:91], v[128:131], v[204:207], v[88:91]
	v_mfma_f32_16x16x32_bf16 v[80:83], v[136:139], v[204:207], v[80:83]
	v_mfma_f32_16x16x32_bf16 v[124:127], v[132:135], v[184:187], v[124:127]
	v_mfma_f32_16x16x32_bf16 v[120:123], v[140:143], v[184:187], v[120:123]
	v_mfma_f32_16x16x32_bf16 v[116:119], v[132:135], v[192:195], v[116:119]
	v_mfma_f32_16x16x32_bf16 v[112:115], v[140:143], v[192:195], v[112:115]
	v_mfma_f32_16x16x32_bf16 v[104:107], v[132:135], v[200:203], v[104:107]
	v_mfma_f32_16x16x32_bf16 v[96:99], v[140:143], v[200:203], v[96:99]
	v_mfma_f32_16x16x32_bf16 v[88:91], v[132:135], v[212:215], v[88:91]
	v_mfma_f32_16x16x32_bf16 v[80:83], v[140:143], v[212:215], v[80:83]
	s_setprio 0
	s_setprio 1
	v_mfma_f32_16x16x32_bf16 v[108:111], v[144:147], v[180:183], v[108:111]
	v_mfma_f32_16x16x32_bf16 v[100:103], v[172:175], v[180:183], v[100:103]
	v_mfma_f32_16x16x32_bf16 v[92:95], v[144:147], v[188:191], v[92:95]
	v_mfma_f32_16x16x32_bf16 v[84:87], v[172:175], v[188:191], v[84:87]
	v_mfma_f32_16x16x32_bf16 v[76:79], v[144:147], v[196:199], v[76:79]
	v_mfma_f32_16x16x32_bf16 v[72:75], v[172:175], v[196:199], v[72:75]
	v_mfma_f32_16x16x32_bf16 v[68:71], v[144:147], v[204:207], v[68:71]
	v_mfma_f32_16x16x32_bf16 v[64:67], v[172:175], v[204:207], v[64:67]
	v_mfma_f32_16x16x32_bf16 v[108:111], v[148:151], v[184:187], v[108:111]
	v_mfma_f32_16x16x32_bf16 v[100:103], v[176:179], v[184:187], v[100:103]
	v_mfma_f32_16x16x32_bf16 v[92:95], v[148:151], v[192:195], v[92:95]
	v_mfma_f32_16x16x32_bf16 v[84:87], v[176:179], v[192:195], v[84:87]
	v_mfma_f32_16x16x32_bf16 v[76:79], v[148:151], v[200:203], v[76:79]
	v_mfma_f32_16x16x32_bf16 v[72:75], v[176:179], v[200:203], v[72:75]
	v_mfma_f32_16x16x32_bf16 v[68:71], v[148:151], v[212:215], v[68:71]
	v_mfma_f32_16x16x32_bf16 v[64:67], v[176:179], v[212:215], v[64:67]
	s_setprio 0
	s_barrier
	s_add_i32 s47, s81, s39
	v_lshl_add_u64 v[216:217], s[66:67], 0, v[156:157]
	s_mov_b32 m0, s47
	ds_read_b128 v[180:183], v210 offset:16384
	ds_read_b128 v[184:187], v210 offset:17408
	ds_read_b128 v[188:191], v210 offset:18432
	ds_read_b128 v[192:195], v210 offset:19456
	ds_read_b128 v[196:199], v210 offset:20480
	ds_read_b128 v[200:203], v210 offset:21504
	ds_read_b128 v[204:207], v210 offset:22528
	ds_read_b128 v[212:215], v210 offset:23552
	global_load_lds_dwordx4 v[216:217], off
	s_add_i32 m0, s47, 0x2000
	s_add_u32 s90, s66, 0x200000
	v_lshl_add_u64 v[218:219], s[66:67], 0, v[160:161]
	s_addc_u32 s91, s67, 0
	s_add_i32 s47, s82, s39
	global_load_lds_dwordx4 v[218:219], off
	v_lshl_add_u64 v[220:221], s[90:91], 0, v[156:157]
	s_mov_b32 m0, s47
	v_lshl_add_u64 v[222:223], s[70:71], 0, v[158:159]
	global_load_lds_dwordx4 v[220:221], off
	v_lshl_add_u64 v[220:221], s[90:91], 0, v[160:161]
	s_add_i32 m0, s47, 0x2000
	s_nop 0
	global_load_lds_dwordx4 v[220:221], off
	v_lshl_add_u64 v[220:221], s[70:71], 0, v[154:155]
	s_mov_b32 m0, s17
	s_nop 0
	global_load_lds_dwordx4 v[220:221], off
	s_mov_b32 m0, s72
	s_nop 0
	global_load_lds_dwordx4 v[222:223], off
	s_waitcnt vmcnt(8)
	s_waitcnt lgkmcnt(0)
	s_barrier
	s_setprio 1
	s_waitcnt lgkmcnt(0)
	v_mfma_f32_16x16x32_bf16 v[60:63], v[128:131], v[180:183], v[60:63]
	v_mfma_f32_16x16x32_bf16 v[56:59], v[136:139], v[180:183], v[56:59]
	v_mfma_f32_16x16x32_bf16 v[52:55], v[128:131], v[188:191], v[52:55]
	v_mfma_f32_16x16x32_bf16 v[48:51], v[136:139], v[188:191], v[48:51]
	v_mfma_f32_16x16x32_bf16 v[40:43], v[128:131], v[196:199], v[40:43]
	v_mfma_f32_16x16x32_bf16 v[32:35], v[136:139], v[196:199], v[32:35]
	v_mfma_f32_16x16x32_bf16 v[24:27], v[128:131], v[204:207], v[24:27]
	v_mfma_f32_16x16x32_bf16 v[16:19], v[136:139], v[204:207], v[16:19]
	v_mfma_f32_16x16x32_bf16 v[60:63], v[132:135], v[184:187], v[60:63]
	v_mfma_f32_16x16x32_bf16 v[56:59], v[140:143], v[184:187], v[56:59]
	v_mfma_f32_16x16x32_bf16 v[52:55], v[132:135], v[192:195], v[52:55]
	v_mfma_f32_16x16x32_bf16 v[48:51], v[140:143], v[192:195], v[48:51]
	v_mfma_f32_16x16x32_bf16 v[40:43], v[132:135], v[200:203], v[40:43]
	v_mfma_f32_16x16x32_bf16 v[32:35], v[140:143], v[200:203], v[32:35]
	v_mfma_f32_16x16x32_bf16 v[24:27], v[132:135], v[212:215], v[24:27]
	v_mfma_f32_16x16x32_bf16 v[16:19], v[140:143], v[212:215], v[16:19]
	s_setprio 0
	s_setprio 1
	v_mfma_f32_16x16x32_bf16 v[44:47], v[144:147], v[180:183], v[44:47]
	v_mfma_f32_16x16x32_bf16 v[36:39], v[172:175], v[180:183], v[36:39]
	v_mfma_f32_16x16x32_bf16 v[28:31], v[144:147], v[188:191], v[28:31]
	v_mfma_f32_16x16x32_bf16 v[20:23], v[172:175], v[188:191], v[20:23]
	v_mfma_f32_16x16x32_bf16 v[12:15], v[144:147], v[196:199], v[12:15]
	v_mfma_f32_16x16x32_bf16 v[8:11], v[172:175], v[196:199], v[8:11]
	v_mfma_f32_16x16x32_bf16 v[4:7], v[144:147], v[204:207], v[4:7]
	v_mfma_f32_16x16x32_bf16 v[0:3], v[172:175], v[204:207], v[0:3]
	v_mfma_f32_16x16x32_bf16 v[44:47], v[148:151], v[184:187], v[44:47]
	v_mfma_f32_16x16x32_bf16 v[36:39], v[176:179], v[184:187], v[36:39]
	v_mfma_f32_16x16x32_bf16 v[28:31], v[148:151], v[192:195], v[28:31]
	v_mfma_f32_16x16x32_bf16 v[20:23], v[176:179], v[192:195], v[20:23]
	v_mfma_f32_16x16x32_bf16 v[12:15], v[148:151], v[200:203], v[12:15]
	v_mfma_f32_16x16x32_bf16 v[8:11], v[176:179], v[200:203], v[8:11]
	v_mfma_f32_16x16x32_bf16 v[4:7], v[148:151], v[212:215], v[4:7]
	v_mfma_f32_16x16x32_bf16 v[0:3], v[176:179], v[212:215], v[0:3]
	s_setprio 0
	s_barrier
; #define PG8_STAGE(bufoff, gbase, voff) do { _Pragma("unroll") for (int _i = 0; _i < 2; ++_i) \
;         __builtin_amdgcn_global_load_lds((const unsigned*)((const char*)(gbase) + (voff)[_i]), (LAS unsigned*)(lds + (bufoff) + ldsw + _i * 8192), 16, 0, 0); } while (0)
; #define PG8_LDA(dst, b, h) do { _Pragma("unroll") for (int m = 0; m < 4; ++m) _Pragma("unroll") for (int k = 0; k < 2; ++k) dst[m][k] = *(const LAS bf16x8*)(lds + PG8_SA(b, h) + aoff + m * 2048 + k * 1024); } while (0)
; #define PG8_LDB(dst, b, h) do { _Pragma("unroll") for (int n = 0; n < 2; ++n) _Pragma("unroll") for (int k = 0; k < 2; ++k) dst[n][k] = *(const LAS bf16x8*)(lds + PG8_SB(b, h) + boff + n * 2048 + k * 1024); } while (0)
; #define PG8_MMA(ai, bj, At, Bt) do { __builtin_amdgcn_s_setprio(1); _Pragma("unroll") for (int m = 0; m < 4; ++m) _Pragma("unroll") for (int n = 0; n < 2; ++n) _Pragma("unroll") for (int k = 0; k < 2; ++k) \
;         acc[ai][bj][m][n] = __builtin_amdgcn_mfma_f32_16x16x32_bf16(Bt[n][k], At[m][k], acc[ai][bj][m][n], 0, 0, 0); __builtin_amdgcn_s_setprio(0); } while (0)
; #define PG8_WAIT_V(n) asm volatile("s_waitcnt vmcnt(" #n ")" ::: "memory")
; #define PG8_WAIT_L(n) asm volatile("s_waitcnt lgkmcnt(" #n ")" ::: "memory")
; #define PG8_BAR __builtin_amdgcn_s_barrier()
; #define PG8_SCHED __builtin_amdgcn_sched_barrier(0)
; template <class Epi, class Sched>
; __device__ __forceinline__ void gemm_phase(LAS unsigned char* lds, const Gemm g, const Sched& S, const Epi& E) {
;     ...
;             PG8_LDB(B0, 1, 0); PG8_LDB(B1, 1, 1); PG8_SCHED; PG8_LDA(At, 1, 0); PG8_STAGE(PG8_SA(0, 1), a2 + hstepA, voffA);
;             PG8_WAIT_V(8); PG8_WAIT_L(0); PG8_BAR; PG8_MMA(0, 0, At, B0); PG8_MMA(0, 1, At, B1); PG8_BAR; PG8_SCHED;
	s_add_i32 s47, 0, 0x18000
	s_add_i32 s57, 0, 0x1c000
	v_add_u32_e32 v140, s47, v153
	v_add_u32_e32 v176, s57, v153
	ds_read_b128 v[128:131], v140
	ds_read_b128 v[132:135], v140 offset:1024
	ds_read_b128 v[136:139], v140 offset:2048
	ds_read_b128 v[140:143], v140 offset:3072
	ds_read_b128 v[144:147], v176
	ds_read_b128 v[148:151], v176 offset:1024
	ds_read_b128 v[172:175], v176 offset:2048
	ds_read_b128 v[176:179], v176 offset:3072
	s_add_u32 s70, s70, 0x200000
	s_addc_u32 s71, s71, 0
	s_mov_b32 m0, s73
	v_lshl_add_u64 v[224:225], s[70:71], 0, v[154:155]
	ds_read_b128 v[180:183], v210 offset:32768
	ds_read_b128 v[184:187], v210 offset:33792
	ds_read_b128 v[188:191], v210 offset:34816
	ds_read_b128 v[192:195], v210 offset:35840
	ds_read_b128 v[196:199], v210 offset:36864
	ds_read_b128 v[200:203], v210 offset:37888
	ds_read_b128 v[204:207], v210 offset:38912
	ds_read_b128 v[212:215], v210 offset:39936
	global_load_lds_dwordx4 v[224:225], off
	v_lshl_add_u64 v[224:225], s[70:71], 0, v[158:159]
	s_mov_b32 m0, s76
	s_nop 0
	global_load_lds_dwordx4 v[224:225], off
	s_waitcnt vmcnt(8)
	s_waitcnt lgkmcnt(0)
	s_barrier
	s_setprio 1
	s_waitcnt lgkmcnt(0)
	v_mfma_f32_16x16x32_bf16 v[124:127], v[128:131], v[180:183], v[124:127]
	v_mfma_f32_16x16x32_bf16 v[120:123], v[136:139], v[180:183], v[120:123]
	v_mfma_f32_16x16x32_bf16 v[116:119], v[128:131], v[188:191], v[116:119]
	v_mfma_f32_16x16x32_bf16 v[112:115], v[136:139], v[188:191], v[112:115]
	v_mfma_f32_16x16x32_bf16 v[104:107], v[128:131], v[196:199], v[104:107]
	v_mfma_f32_16x16x32_bf16 v[96:99], v[136:139], v[196:199], v[96:99]
	v_mfma_f32_16x16x32_bf16 v[88:91], v[128:131], v[204:207], v[88:91]
	v_mfma_f32_16x16x32_bf16 v[80:83], v[136:139], v[204:207], v[80:83]
	v_mfma_f32_16x16x32_bf16 v[124:127], v[132:135], v[184:187], v[124:127]
	v_mfma_f32_16x16x32_bf16 v[120:123], v[140:143], v[184:187], v[120:123]
	v_mfma_f32_16x16x32_bf16 v[116:119], v[132:135], v[192:195], v[116:119]
	v_mfma_f32_16x16x32_bf16 v[112:115], v[140:143], v[192:195], v[112:115]
	v_mfma_f32_16x16x32_bf16 v[104:107], v[132:135], v[200:203], v[104:107]
	v_mfma_f32_16x16x32_bf16 v[96:99], v[140:143], v[200:203], v[96:99]
	v_mfma_f32_16x16x32_bf16 v[88:91], v[132:135], v[212:215], v[88:91]
	v_mfma_f32_16x16x32_bf16 v[80:83], v[140:143], v[212:215], v[80:83]
	s_setprio 0
	s_setprio 1
	v_mfma_f32_16x16x32_bf16 v[108:111], v[144:147], v[180:183], v[108:111]
	v_mfma_f32_16x16x32_bf16 v[100:103], v[172:175], v[180:183], v[100:103]
	v_mfma_f32_16x16x32_bf16 v[92:95], v[144:147], v[188:191], v[92:95]
	v_mfma_f32_16x16x32_bf16 v[84:87], v[172:175], v[188:191], v[84:87]
	v_mfma_f32_16x16x32_bf16 v[76:79], v[144:147], v[196:199], v[76:79]
	v_mfma_f32_16x16x32_bf16 v[72:75], v[172:175], v[196:199], v[72:75]
	v_mfma_f32_16x16x32_bf16 v[68:71], v[144:147], v[204:207], v[68:71]
	v_mfma_f32_16x16x32_bf16 v[64:67], v[172:175], v[204:207], v[64:67]
	v_mfma_f32_16x16x32_bf16 v[108:111], v[148:151], v[184:187], v[108:111]
	v_mfma_f32_16x16x32_bf16 v[100:103], v[176:179], v[184:187], v[100:103]
	v_mfma_f32_16x16x32_bf16 v[92:95], v[148:151], v[192:195], v[92:95]
	v_mfma_f32_16x16x32_bf16 v[84:87], v[176:179], v[192:195], v[84:87]
	v_mfma_f32_16x16x32_bf16 v[76:79], v[148:151], v[200:203], v[76:79]
	v_mfma_f32_16x16x32_bf16 v[72:75], v[176:179], v[200:203], v[72:75]
	v_mfma_f32_16x16x32_bf16 v[68:71], v[148:151], v[212:215], v[68:71]
	v_mfma_f32_16x16x32_bf16 v[64:67], v[176:179], v[212:215], v[64:67]
	s_setprio 0
	s_barrier
; #define PG8_STAGE(bufoff, gbase, voff) do { _Pragma("unroll") for (int _i = 0; _i < 2; ++_i) \
;         __builtin_amdgcn_global_load_lds((const unsigned*)((const char*)(gbase) + (voff)[_i]), (LAS unsigned*)(lds + (bufoff) + ldsw + _i * 8192), 16, 0, 0); } while (0)
; #define PG8_LDA(dst, b, h) do { _Pragma("unroll") for (int m = 0; m < 4; ++m) _Pragma("unroll") for (int k = 0; k < 2; ++k) dst[m][k] = *(const LAS bf16x8*)(lds + PG8_SA(b, h) + aoff + m * 2048 + k * 1024); } while (0)
; #define PG8_MMA(ai, bj, At, Bt) do { __builtin_amdgcn_s_setprio(1); _Pragma("unroll") for (int m = 0; m < 4; ++m) _Pragma("unroll") for (int n = 0; n < 2; ++n) _Pragma("unroll") for (int k = 0; k < 2; ++k) \
;         acc[ai][bj][m][n] = __builtin_amdgcn_mfma_f32_16x16x32_bf16(Bt[n][k], At[m][k], acc[ai][bj][m][n], 0, 0, 0); __builtin_amdgcn_s_setprio(0); } while (0)
; #define PG8_WAIT_V(n) asm volatile("s_waitcnt vmcnt(" #n ")" ::: "memory")
; #define PG8_WAIT_L(n) asm volatile("s_waitcnt lgkmcnt(" #n ")" ::: "memory")
; #define PG8_BAR __builtin_amdgcn_s_barrier()
; #define PG8_SCHED __builtin_amdgcn_sched_barrier(0)
; template <class Epi, class Sched>
; __device__ __forceinline__ void gemm_phase(LAS unsigned char* lds, const Gemm g, const Sched& S, const Epi& E) {
;     ...
;             PG8_LDA(At, 1, 1); PG8_STAGE(PG8_SB(1, 0), b3, voffB); PG8_STAGE(PG8_SB(1, 1), b3 + hstepB, voffB); PG8_STAGE(PG8_SA(1, 0), a3, voffA);
;             PG8_WAIT_V(8); PG8_WAIT_L(0); PG8_BAR; PG8_MMA(1, 0, At, B0); PG8_MMA(1, 1, At, B1); PG8_BAR; PG8_SCHED;
;         }
	s_add_i32 s47, s47, s39
	v_lshl_add_u64 v[216:217], v[216:217], 0, s[24:25]
	s_mov_b32 m0, s47
	ds_read_b128 v[180:183], v210 offset:49152
	ds_read_b128 v[184:187], v210 offset:50176
	ds_read_b128 v[188:191], v210 offset:51200
	ds_read_b128 v[192:195], v210 offset:52224
	ds_read_b128 v[196:199], v210 offset:53248
	ds_read_b128 v[200:203], v210 offset:54272
	ds_read_b128 v[204:207], v210 offset:55296
	ds_read_b128 v[212:215], v210 offset:56320
	global_load_lds_dwordx4 v[216:217], off
	s_add_i32 m0, s47, 0x2000
	s_add_u32 s66, s66, 0x200080
	v_lshl_add_u64 v[216:217], v[218:219], 0, s[24:25]
	s_addc_u32 s67, s67, 0
	s_add_i32 s47, s57, s39
	global_load_lds_dwordx4 v[216:217], off
	v_lshl_add_u64 v[216:217], s[66:67], 0, v[156:157]
	s_mov_b32 m0, s47
	s_nop 0
	global_load_lds_dwordx4 v[216:217], off
	v_lshl_add_u64 v[216:217], s[66:67], 0, v[160:161]
	s_add_i32 m0, s47, 0x2000
	s_nop 0
	global_load_lds_dwordx4 v[216:217], off
	v_lshl_add_u64 v[216:217], v[220:221], 0, s[98:99]
	s_mov_b32 m0, s79
	s_nop 0
	global_load_lds_dwordx4 v[216:217], off
	v_lshl_add_u64 v[216:217], v[222:223], 0, s[98:99]
	s_mov_b32 m0, s80
	s_nop 0
	global_load_lds_dwordx4 v[216:217], off
	s_waitcnt vmcnt(8)
	s_waitcnt lgkmcnt(0)
	s_barrier
	s_setprio 1
	s_waitcnt lgkmcnt(0)
	v_mfma_f32_16x16x32_bf16 v[60:63], v[128:131], v[180:183], v[60:63]
	v_mfma_f32_16x16x32_bf16 v[56:59], v[136:139], v[180:183], v[56:59]
	v_mfma_f32_16x16x32_bf16 v[52:55], v[128:131], v[188:191], v[52:55]
	v_mfma_f32_16x16x32_bf16 v[48:51], v[136:139], v[188:191], v[48:51]
	v_mfma_f32_16x16x32_bf16 v[40:43], v[128:131], v[196:199], v[40:43]
	v_mfma_f32_16x16x32_bf16 v[32:35], v[136:139], v[196:199], v[32:35]
	v_mfma_f32_16x16x32_bf16 v[24:27], v[128:131], v[204:207], v[24:27]
	v_mfma_f32_16x16x32_bf16 v[16:19], v[136:139], v[204:207], v[16:19]
	v_mfma_f32_16x16x32_bf16 v[60:63], v[132:135], v[184:187], v[60:63]
	v_mfma_f32_16x16x32_bf16 v[56:59], v[140:143], v[184:187], v[56:59]
	v_mfma_f32_16x16x32_bf16 v[52:55], v[132:135], v[192:195], v[52:55]
	v_mfma_f32_16x16x32_bf16 v[48:51], v[140:143], v[192:195], v[48:51]
	v_mfma_f32_16x16x32_bf16 v[40:43], v[132:135], v[200:203], v[40:43]
	v_mfma_f32_16x16x32_bf16 v[32:35], v[140:143], v[200:203], v[32:35]
	v_mfma_f32_16x16x32_bf16 v[24:27], v[132:135], v[212:215], v[24:27]
	v_mfma_f32_16x16x32_bf16 v[16:19], v[140:143], v[212:215], v[16:19]
	s_setprio 0
	s_setprio 1
	v_mfma_f32_16x16x32_bf16 v[44:47], v[144:147], v[180:183], v[44:47]
	v_mfma_f32_16x16x32_bf16 v[36:39], v[172:175], v[180:183], v[36:39]
	v_mfma_f32_16x16x32_bf16 v[28:31], v[144:147], v[188:191], v[28:31]
	v_mfma_f32_16x16x32_bf16 v[20:23], v[172:175], v[188:191], v[20:23]
	v_mfma_f32_16x16x32_bf16 v[12:15], v[144:147], v[196:199], v[12:15]
	v_mfma_f32_16x16x32_bf16 v[8:11], v[172:175], v[196:199], v[8:11]
	v_mfma_f32_16x16x32_bf16 v[4:7], v[144:147], v[204:207], v[4:7]
	v_mfma_f32_16x16x32_bf16 v[0:3], v[172:175], v[204:207], v[0:3]
	v_mfma_f32_16x16x32_bf16 v[44:47], v[148:151], v[184:187], v[44:47]
	v_mfma_f32_16x16x32_bf16 v[36:39], v[176:179], v[184:187], v[36:39]
	v_mfma_f32_16x16x32_bf16 v[28:31], v[148:151], v[192:195], v[28:31]
	v_mfma_f32_16x16x32_bf16 v[20:23], v[176:179], v[192:195], v[20:23]
	v_mfma_f32_16x16x32_bf16 v[12:15], v[148:151], v[200:203], v[12:15]
	v_mfma_f32_16x16x32_bf16 v[8:11], v[176:179], v[200:203], v[8:11]
	v_mfma_f32_16x16x32_bf16 v[4:7], v[148:151], v[212:215], v[4:7]
	v_mfma_f32_16x16x32_bf16 v[0:3], v[176:179], v[212:215], v[0:3]
	s_setprio 0
	s_barrier
	s_add_u32 s8, s8, 0x1000
	s_addc_u32 s9, s9, 0
	s_add_u32 s41, s41, 0x100
	s_addc_u32 s46, s46, 0
	s_cmp_ge_i32 s55, s4
	s_mov_b32 s47, s55
	s_cbranch_scc0 .LBB0_917
	s_and_b64 vcc, exec, s[36:37]
	s_cbranch_vccz .LBB0_922
	s_barrier
	s_cmp_lt_i32 s12, 0
	s_mov_b64 s[8:9], -1
	s_cbranch_scc1 .LBB0_923

; __global__ void __launch_bounds__(512, 2) fwd(Args a) {
	.amdhsa_kernel _Z3fwd4Args
		.amdhsa_group_segment_fixed_size 0
		.amdhsa_private_segment_fixed_size 0
		.amdhsa_kernarg_size 472
		.amdhsa_user_sgpr_count 2
		.amdhsa_user_sgpr_dispatch_ptr 0
		.amdhsa_user_sgpr_queue_ptr 0
		.amdhsa_user_sgpr_kernarg_segment_ptr 1
		.amdhsa_user_sgpr_dispatch_id 0
		.amdhsa_user_sgpr_kernarg_preload_length 0
		.amdhsa_user_sgpr_kernarg_preload_offset 0
		.amdhsa_user_sgpr_private_segment_size 0
		.amdhsa_uses_dynamic_stack 0
		.amdhsa_enable_private_segment 0
		.amdhsa_system_sgpr_workgroup_id_x 1
		.amdhsa_system_sgpr_workgroup_id_y 0
		.amdhsa_system_sgpr_workgroup_id_z 0
		.amdhsa_system_sgpr_workgroup_info 0
		.amdhsa_system_vgpr_workitem_id 2
		.amdhsa_next_free_vgpr 243
		.amdhsa_next_free_sgpr 102
		.amdhsa_accum_offset 244
		.amdhsa_reserve_vcc 1
		.amdhsa_float_round_mode_32 0
		.amdhsa_float_round_mode_16_64 0
		.amdhsa_float_denorm_mode_32 3
		.amdhsa_float_denorm_mode_16_64 3
		.amdhsa_dx10_clamp 1
		.amdhsa_ieee_mode 1
		.amdhsa_fp16_overflow 0
		.amdhsa_tg_split 0
		.amdhsa_exception_fp_ieee_invalid_op 0
		.amdhsa_exception_fp_denorm_src 0
		.amdhsa_exception_fp_ieee_div_zero 0
		.amdhsa_exception_fp_ieee_overflow 0
		.amdhsa_exception_fp_ieee_underflow 0
		.amdhsa_exception_fp_ieee_inexact 0
		.amdhsa_exception_int_div_zero 0
	.end_amdhsa_kernel

; __global__ void __launch_bounds__(512, 2) fwd(Args a) {
amdhsa.kernels:
  - .agpr_count:     0
    .args:
      - .offset:         0
        .size:           216
        .value_kind:     by_value
      - .offset:         216
        .size:           4
        .value_kind:     hidden_block_count_x
      - .offset:         220
        .size:           4
        .value_kind:     hidden_block_count_y
      - .offset:         224
        .size:           4
        .value_kind:     hidden_block_count_z
      - .offset:         228
        .size:           2
        .value_kind:     hidden_group_size_x
      - .offset:         230
        .size:           2
        .value_kind:     hidden_group_size_y
      - .offset:         232
        .size:           2
        .value_kind:     hidden_group_size_z
      - .offset:         234
        .size:           2
        .value_kind:     hidden_remainder_x
      - .offset:         236
        .size:           2
        .value_kind:     hidden_remainder_y
      - .offset:         238
        .size:           2
        .value_kind:     hidden_remainder_z
      - .offset:         256
        .size:           8
        .value_kind:     hidden_global_offset_x
      - .offset:         264
        .size:           8
        .value_kind:     hidden_global_offset_y
      - .offset:         272
        .size:           8
        .value_kind:     hidden_global_offset_z
      - .offset:         280
        .size:           2
        .value_kind:     hidden_grid_dims
      - .offset:         304
        .size:           8
        .value_kind:     hidden_multigrid_sync_arg
      - .offset:         336
        .size:           4
        .value_kind:     hidden_dynamic_lds_size
    .group_segment_fixed_size: 0
    .kernarg_segment_align: 8
    .kernarg_segment_size: 472
    .language:       OpenCL C
    .language_version:
      - 2
      - 0
    .max_flat_workgroup_size: 512
    .name:           _Z3fwd4Args
    .private_segment_fixed_size: 0
    .sgpr_count:     108
    .sgpr_spill_count: 38
    .symbol:         _Z3fwd4Args.kd
    .uniform_work_group_size: 1
    .uses_dynamic_stack: false
    .vgpr_count:     243
    .vgpr_spill_count: 0
    .wavefront_size: 64
